# combination: barrier polls top generation word, P1 ctx projection placement (2 sleeps), LRU pass-2 mid-item wait only for carry loads
# speedup vs baseline: 1.0074x; 1.0012x over previous
; template <int PASS>
; __device__ __forceinline__ void lru_item(Frame& F, const LAS bf16* lw, const LAS float* prm, const LAS float* cwl, LAS float* xs, LAS unsigned char* pf, int head, int item, int nitem) {
;     const int rc = item & 7, col = (item >> 3) % 65, b = (item >> 3) / 65;
;     int lane = F.lane; asm volatile("" : "+v"(lane));
;     const int t = lane & 31, hh = lane >> 5;
;     const int r0 = rc * 32, r = r0 + t;
;     const int q = (col < 64) ? (8 + col * 8 + rc) : rc;
;     asm volatile("s_waitcnt vmcnt(0)" ::: "memory");
;     u32x4 vw[4][4];
; #pragma unroll
;     for (int k = 0; k < 4; ++k) {
;         const int rr = r - 1 + k; const bool ok = (rr >= 0) && (rr < 256);
;         const int row = t + k;
; #pragma unroll
;         for (int ks = 0; ks < 4; ++ks) { u32x4 w = *(const LAS u32x4*)(pf + row * 128 + (((2 * ks + hh) ^ ((row >> 1) & 7)) * 16)); if (!ok) w = (u32x4){0u, 0u, 0u, 0u}; vw[k][ks] = w; }
;     }
;     LDS_WAIT(); asm volatile("" ::: "memory");
;     if (nitem >= 0) lru_prefetch(F.ws, pf, lane, head, nitem);
;     float lc[2][2]; u32x4 gq[4];
;     const size_t tok = (size_t)b * SEQ + (size_t)r * 64 + col;
;     if (PASS == 2) {
; #pragma unroll
;         for (int d = 0; d < 2; ++d)
; #pragma unroll
;             for (int ct = 0; ct < 2; ++ct) lc[d][ct] = ((const float*)(F.ws + WS_LC))[(size_t)((b * 2 + d) * NQ + q) * 1024 + head * 64 + t + 32 * ct];
;     }
;     float xa[4][8];
; #pragma unroll
;     for (int ks = 0; ks < 4; ++ks) {
;         const int ch = 16 * ks + 8 * hh;
;         const f32x4 b0 = *(const LAS f32x4*)(cwl + 4 * 64 + ch), b1 = *(const LAS f32x4*)(cwl + 4 * 64 + ch + 4);
; #pragma unroll
;         for (int j = 0; j < 4; ++j) { xa[ks][j] = b0[j]; xa[ks][4 + j] = b1[j]; }
;     }
; #pragma unroll
;     for (int k = 0; k < 4; ++k)
; #pragma unroll
;         for (int ks = 0; ks < 4; ++ks) {
;             const u32x4 w = vw[k][ks]; const int ch = 16 * ks + 8 * hh;
;             const f32x4 c0 = *(const LAS f32x4*)(cwl + k * 64 + ch), c1 = *(const LAS f32x4*)(cwl + k * 64 + ch + 4);
;             xa[ks][0] += c0[0] * bf_lo(w.x); xa[ks][1] += c0[1] * bf_hi(w.x); xa[ks][2] += c0[2] * bf_lo(w.y); xa[ks][3] += c0[3] * bf_hi(w.y);
;             xa[ks][4] += c1[0] * bf_lo(w.z); xa[ks][5] += c1[1] * bf_hi(w.z); xa[ks][6] += c1[2] * bf_lo(w.w); xa[ks][7] += c1[3] * bf_hi(w.w);
.LBB0_902:
	s_ashr_i32 s4, s62, 3
	s_mul_hi_i32 s16, s4, 0x7e07e07f
	s_lshr_b32 s17, s16, 31
	s_ashr_i32 s16, s16, 5
	s_add_i32 s18, s16, s17
	s_mul_i32 s16, s18, 0x41
	s_sub_i32 s4, s4, s16
	s_lshl_b32 s16, s4, 3
	s_xor_b64 s[12:13], s[12:13], -1
	s_add_i32 s16, s16, 8
	s_cmp_lt_i32 s4, 64
	s_cselect_b32 s16, s16, 0
	s_and_b32 s17, s62, 7
	s_ashr_i32 s19, s18, 31
	s_or_b32 s28, s16, s17
	v_lshl_or_b32 v64, s17, 5, v121
	s_lshl_b64 s[16:17], s[18:19], 14
	s_ashr_i32 s19, s4, 31
	s_add_u32 s16, s16, s4
	s_mul_i32 s4, s18, 0x410
	s_addc_u32 s17, s17, s19
	s_add_i32 s18, s28, s4
	v_cmp_gt_u32_e32 vcc, s49, v64
	s_ashr_i32 s19, s18, 31
	s_lshl_b64 s[28:29], s[18:19], 12
	s_waitcnt lgkmcnt(0)
	v_cndmask_b32_e32 v122, 0, v63, vcc
	v_cndmask_b32_e32 v124, 0, v62, vcc
	v_cndmask_b32_e32 v125, 0, v61, vcc
	v_cndmask_b32_e32 v129, 0, v60, vcc
	v_cndmask_b32_e32 v132, 0, v59, vcc
	v_cndmask_b32_e32 v135, 0, v58, vcc
	v_cndmask_b32_e32 v136, 0, v57, vcc
	v_cndmask_b32_e32 v139, 0, v56, vcc
	v_cndmask_b32_e32 v145, 0, v55, vcc
	v_cndmask_b32_e32 v180, 0, v54, vcc
	v_cndmask_b32_e32 v181, 0, v53, vcc
	v_cndmask_b32_e32 v182, 0, v52, vcc
	v_cndmask_b32_e32 v183, 0, v51, vcc
	v_cndmask_b32_e32 v184, 0, v50, vcc
	v_cndmask_b32_e32 v185, 0, v49, vcc
	v_cndmask_b32_e32 v186, 0, v48, vcc
	v_cmp_eq_u32_e32 vcc, s37, v64
	s_addk_i32 s18, 0x208
	v_lshlrev_b32_e32 v88, 2, v121
	v_cndmask_b32_e64 v123, v47, 0, vcc
	v_cndmask_b32_e64 v126, v46, 0, vcc
	v_cndmask_b32_e64 v128, v45, 0, vcc
	v_cndmask_b32_e64 v130, v44, 0, vcc
	v_cndmask_b32_e64 v134, v43, 0, vcc
	v_cndmask_b32_e64 v137, v42, 0, vcc
	v_cndmask_b32_e64 v187, v41, 0, vcc
	v_cndmask_b32_e64 v188, v40, 0, vcc
	v_cndmask_b32_e64 v189, v39, 0, vcc
	v_cndmask_b32_e64 v190, v38, 0, vcc
	v_cndmask_b32_e64 v191, v37, 0, vcc
	v_cndmask_b32_e64 v192, v36, 0, vcc
	v_cndmask_b32_e64 v193, v35, 0, vcc
	v_cndmask_b32_e64 v194, v34, 0, vcc
	v_cndmask_b32_e64 v195, v33, 0, vcc
	v_cndmask_b32_e64 v196, v32, 0, vcc
	v_cmp_eq_u32_e32 vcc, 0, v64
	s_ashr_i32 s19, s18, 31
	s_lshl_b64 s[18:19], s[18:19], 12
	v_cndmask_b32_e64 v201, v13, 0, vcc
	v_cndmask_b32_e64 v202, v12, 0, vcc
	v_lshl_add_u64 v[12:13], s[6:7], 0, v[88:89]
	v_and_b32_e32 v127, 0xffffffe0, v144
	v_cndmask_b32_e64 v84, v15, 0, vcc
	v_cndmask_b32_e64 v85, v14, 0, vcc
	v_lshl_add_u64 v[14:15], v[12:13], 0, s[28:29]
	v_lshl_add_u64 v[12:13], v[12:13], 0, s[18:19]
	v_add_u32_e32 v138, 0, v127
	v_cndmask_b32_e64 v131, v29, 0, vcc
	v_cndmask_b32_e64 v133, v28, 0, vcc
	v_cndmask_b32_e64 v92, v31, 0, vcc
	v_cndmask_b32_e64 v93, v30, 0, vcc
	v_cndmask_b32_e64 v197, v21, 0, vcc
	v_cndmask_b32_e64 v198, v20, 0, vcc
	v_cndmask_b32_e64 v94, v23, 0, vcc
	v_cndmask_b32_e64 v95, v22, 0, vcc
	v_cndmask_b32_e64 v199, v17, 0, vcc
	v_cndmask_b32_e64 v200, v16, 0, vcc
	v_cndmask_b32_e64 v96, v19, 0, vcc
	v_cndmask_b32_e64 v97, v18, 0, vcc
	v_lshlrev_b32_e32 v90, 6, v64
	global_load_dword v117, v[14:15], off
	global_load_dword v119, v[14:15], off offset:128
	global_load_dword v118, v[12:13], off
	global_load_dword v120, v[12:13], off offset:128
	ds_read_b128 v[32:35], v138 offset:39424
	ds_read_b128 v[80:83], v138 offset:39440
	ds_read_b128 v[68:71], v138 offset:39488
	ds_read_b128 v[56:59], v138 offset:39504
	ds_read_b128 v[44:47], v138 offset:39552
	ds_read_b128 v[28:31], v138 offset:39568
	ds_read_b128 v[16:19], v138 offset:39616
	ds_read_b128 v[12:15], v138 offset:39632
	ds_read_b128 v[140:143], v138 offset:38400
	ds_read_b128 v[36:39], v138 offset:38416
	ds_read_b128 v[72:75], v138 offset:38464
	ds_read_b128 v[40:43], v138 offset:38480
	ds_read_b128 v[48:51], v138 offset:38528
	ds_read_b128 v[52:55], v138 offset:38544
	ds_read_b128 v[146:149], v138 offset:38656
	ds_read_b128 v[60:63], v138 offset:38672
	ds_read_b128 v[20:23], v138 offset:38592
	ds_read_b128 v[64:67], v138 offset:38608
	v_lshlrev_b32_e32 v77, 16, v26
	v_lshlrev_b32_e32 v76, 16, v85
	s_waitcnt lgkmcnt(0)
	v_mov_b32_e32 v78, v36
	v_mov_b32_e32 v79, v60
	v_pk_mul_f32 v[174:175], v[78:79], v[76:77]
	v_and_b32_e32 v77, 0xffff0000, v26
	v_and_b32_e32 v76, 0xffff0000, v85
	v_mov_b32_e32 v60, v37
	v_pk_mul_f32 v[176:177], v[60:61], v[76:77]
	v_lshlrev_b32_e32 v37, 16, v27
	v_lshlrev_b32_e32 v36, 16, v84
	v_mov_b32_e32 v60, v38
	v_mov_b32_e32 v61, v62
	v_pk_mul_f32 v[178:179], v[60:61], v[36:37]
	v_and_b32_e32 v26, 0xffff0000, v84
	v_mov_b32_e32 v62, v39
	ds_read_b128 v[84:87], v138 offset:38720
	ds_read_b128 v[36:39], v138 offset:38736
	v_and_b32_e32 v27, 0xffff0000, v27
	v_pk_mul_f32 v[26:27], v[62:63], v[26:27]
	v_lshlrev_b32_e32 v61, 16, v10
	v_lshlrev_b32_e32 v60, 16, v97
	v_mov_b32_e32 v62, v40
	s_waitcnt lgkmcnt(0)
	v_mov_b32_e32 v63, v36
	v_pk_mul_f32 v[110:111], v[62:63], v[60:61]
	v_and_b32_e32 v61, 0xffff0000, v10
	v_and_b32_e32 v60, 0xffff0000, v97
	v_mov_b32_e32 v36, v41
	v_pk_mul_f32 v[112:113], v[36:37], v[60:61]
	ds_read_b128 v[60:63], v138 offset:38784
	ds_read_b128 v[76:79], v138 offset:38800
	v_lshlrev_b32_e32 v37, 16, v11
	v_lshlrev_b32_e32 v36, 16, v96
	v_mov_b32_e32 v40, v42
	v_mov_b32_e32 v41, v38
	v_and_b32_e32 v11, 0xffff0000, v11
	v_and_b32_e32 v10, 0xffff0000, v96
	v_mov_b32_e32 v38, v43
	v_pk_mul_f32 v[106:107], v[40:41], v[36:37]
	v_pk_mul_f32 v[108:109], v[38:39], v[10:11]
	v_lshlrev_b32_e32 v11, 16, v6
	v_lshlrev_b32_e32 v10, 16, v95
	v_mov_b32_e32 v36, v52
	s_waitcnt lgkmcnt(0)
; #define LAS __attribute__((address_space(3)))
; __device__ __forceinline__ float bf_lo(unsigned w) { return __uint_as_float(w << 16); }
; __device__ __forceinline__ float bf_hi(unsigned w) { return __uint_as_float(w & 0xffff0000u); }
; template <int PASS>
; __device__ __forceinline__ void lru_item(Frame& F, const LAS bf16* lw, const LAS float* prm, const LAS float* cwl, LAS float* xs, LAS unsigned char* pf, int head, int item, int nitem) {
;     ...
; #pragma unroll
;     for (int k = 0; k < 4; ++k)
; #pragma unroll
;         for (int ks = 0; ks < 4; ++ks) {
;             const u32x4 w = vw[k][ks]; const int ch = 16 * ks + 8 * hh;
;             const f32x4 c0 = *(const LAS f32x4*)(cwl + k * 64 + ch), c1 = *(const LAS f32x4*)(cwl + k * 64 + ch + 4);
;             xa[ks][0] += c0[0] * bf_lo(w.x); xa[ks][1] += c0[1] * bf_hi(w.x); xa[ks][2] += c0[2] * bf_lo(w.y); xa[ks][3] += c0[3] * bf_hi(w.y);
;             xa[ks][4] += c1[0] * bf_lo(w.z); xa[ks][5] += c1[1] * bf_hi(w.z); xa[ks][6] += c1[2] * bf_lo(w.w); xa[ks][7] += c1[3] * bf_hi(w.w);
;         }
	v_mov_b32_e32 v37, v76
	v_pk_mul_f32 v[102:103], v[36:37], v[10:11]
	v_and_b32_e32 v11, 0xffff0000, v6
	v_and_b32_e32 v10, 0xffff0000, v95
	v_mov_b32_e32 v76, v53
	v_pk_mul_f32 v[104:105], v[76:77], v[10:11]
	v_lshlrev_b32_e32 v11, 16, v7
	v_lshlrev_b32_e32 v10, 16, v94
	v_mov_b32_e32 v36, v54
	v_mov_b32_e32 v37, v78
	v_pk_mul_f32 v[98:99], v[36:37], v[10:11]
	ds_read_b128 v[40:43], v138 offset:38848
	ds_read_b128 v[36:39], v138 offset:38864
	v_and_b32_e32 v7, 0xffff0000, v7
	v_and_b32_e32 v6, 0xffff0000, v94
	v_mov_b32_e32 v78, v55
	v_pk_mul_f32 v[100:101], v[78:79], v[6:7]
	v_lshlrev_b32_e32 v7, 16, v2
	v_lshlrev_b32_e32 v6, 16, v93
	v_mov_b32_e32 v10, v64
	s_waitcnt lgkmcnt(0)
	v_mov_b32_e32 v11, v36
	v_pk_mul_f32 v[94:95], v[10:11], v[6:7]
	v_and_b32_e32 v7, 0xffff0000, v2
	v_and_b32_e32 v6, 0xffff0000, v93
	v_mov_b32_e32 v36, v65
	v_pk_mul_f32 v[96:97], v[36:37], v[6:7]
	v_lshlrev_b32_e32 v7, 16, v3
	v_mov_b32_e32 v11, v38
	v_and_b32_e32 v3, 0xffff0000, v3
	v_and_b32_e32 v2, 0xffff0000, v92
	v_mov_b32_e32 v38, v67
	v_lshlrev_b32_e32 v6, 16, v92
	v_mov_b32_e32 v10, v66
	v_pk_mul_f32 v[92:93], v[38:39], v[2:3]
	ds_read_b128 v[150:153], v138 offset:38912
	ds_read_b128 v[154:157], v138 offset:38928
	ds_read_b128 v[158:161], v138 offset:38976
	ds_read_b128 v[162:165], v138 offset:38992
	ds_read_b128 v[76:79], v138 offset:39040
	ds_read_b128 v[64:67], v138 offset:39056
	ds_read_b128 v[52:55], v138 offset:39104
	ds_read_b128 v[36:39], v138 offset:39120
	ds_read_b128 v[166:169], v138 offset:39168
	ds_read_b128 v[170:173], v138 offset:39184
	v_lshlrev_b32_e32 v2, 16, v202
	v_and_b32_e32 v3, 0xffff0000, v202
	v_pk_mul_f32 v[10:11], v[10:11], v[6:7]
	v_pk_fma_f32 v[2:3], v[140:141], v[2:3], v[32:33]
	v_lshlrev_b32_e32 v6, 16, v24
	v_and_b32_e32 v7, 0xffff0000, v24
	v_pk_fma_f32 v[2:3], v[146:147], v[6:7], v[2:3]
	v_lshlrev_b32_e32 v6, 16, v196
	v_and_b32_e32 v7, 0xffff0000, v196
	s_waitcnt lgkmcnt(0)
	v_pk_fma_f32 v[2:3], v[150:151], v[6:7], v[2:3]
	v_lshlrev_b32_e32 v6, 16, v186
	v_and_b32_e32 v7, 0xffff0000, v186
	v_pk_fma_f32 v[32:33], v[166:167], v[6:7], v[2:3]
	v_lshlrev_b32_e32 v2, 16, v201
	v_and_b32_e32 v3, 0xffff0000, v201
	v_pk_fma_f32 v[2:3], v[142:143], v[2:3], v[34:35]
	v_lshlrev_b32_e32 v6, 16, v25
	v_and_b32_e32 v7, 0xffff0000, v25
	v_pk_fma_f32 v[2:3], v[148:149], v[6:7], v[2:3]
	v_lshlrev_b32_e32 v6, 16, v195
	v_and_b32_e32 v7, 0xffff0000, v195
	v_pk_fma_f32 v[2:3], v[152:153], v[6:7], v[2:3]
	v_lshlrev_b32_e32 v6, 16, v185
	v_and_b32_e32 v7, 0xffff0000, v185
	v_pk_fma_f32 v[34:35], v[168:169], v[6:7], v[2:3]
	v_lshlrev_b32_e32 v3, 16, v184
	v_lshlrev_b32_e32 v2, 16, v194
	v_mov_b32_e32 v6, v154
	v_mov_b32_e32 v7, v170
	v_pk_mul_f32 v[2:3], v[6:7], v[2:3]
	v_and_b32_e32 v7, 0xffff0000, v184
	v_and_b32_e32 v6, 0xffff0000, v194
	v_mov_b32_e32 v170, v155
	v_mov_b32_e32 v24, v174
	v_mov_b32_e32 v25, v176
	v_pk_mul_f32 v[6:7], v[170:171], v[6:7]
	v_pk_add_f32 v[24:25], v[80:81], v[24:25]
	v_mov_b32_e32 v176, v175
	v_pk_add_f32 v[24:25], v[24:25], v[176:177]
	v_mov_b32_e32 v80, v2
	v_mov_b32_e32 v81, v6
	v_pk_add_f32 v[24:25], v[24:25], v[80:81]
	v_mov_b32_e32 v6, v3
	v_pk_add_f32 v[24:25], v[24:25], v[6:7]
	v_lshlrev_b32_e32 v3, 16, v183
	v_lshlrev_b32_e32 v2, 16, v193
	v_mov_b32_e32 v6, v156
	v_mov_b32_e32 v7, v172
	v_pk_mul_f32 v[2:3], v[6:7], v[2:3]
	v_and_b32_e32 v7, 0xffff0000, v183
	v_and_b32_e32 v6, 0xffff0000, v193
	v_mov_b32_e32 v172, v157
	v_mov_b32_e32 v80, v178
	v_mov_b32_e32 v81, v26
	v_pk_mul_f32 v[6:7], v[172:173], v[6:7]
	v_pk_add_f32 v[80:81], v[82:83], v[80:81]
	v_mov_b32_e32 v26, v179
	v_pk_add_f32 v[26:27], v[80:81], v[26:27]
	v_mov_b32_e32 v80, v2
	v_mov_b32_e32 v81, v6
	v_pk_add_f32 v[26:27], v[26:27], v[80:81]
	v_mov_b32_e32 v6, v3
	ds_read_b128 v[80:83], v138 offset:39232
	ds_read_b128 v[140:143], v138 offset:39248
	v_lshlrev_b32_e32 v2, 16, v200
	v_and_b32_e32 v3, 0xffff0000, v200
	v_pk_add_f32 v[26:27], v[26:27], v[6:7]
	v_pk_fma_f32 v[2:3], v[72:73], v[2:3], v[68:69]
	v_lshlrev_b32_e32 v6, 16, v8
	v_and_b32_e32 v7, 0xffff0000, v8
	v_pk_fma_f32 v[2:3], v[84:85], v[6:7], v[2:3]
	v_lshlrev_b32_e32 v6, 16, v192
	v_and_b32_e32 v7, 0xffff0000, v192
	v_pk_fma_f32 v[2:3], v[158:159], v[6:7], v[2:3]
	v_lshlrev_b32_e32 v6, 16, v182
	v_and_b32_e32 v7, 0xffff0000, v182
	s_waitcnt lgkmcnt(0)
	v_pk_fma_f32 v[6:7], v[80:81], v[6:7], v[2:3]
	v_lshlrev_b32_e32 v2, 16, v199
	v_and_b32_e32 v3, 0xffff0000, v199
	v_pk_fma_f32 v[2:3], v[74:75], v[2:3], v[70:71]
	v_lshlrev_b32_e32 v8, 16, v9
	v_and_b32_e32 v9, 0xffff0000, v9
	v_pk_fma_f32 v[2:3], v[86:87], v[8:9], v[2:3]
	v_lshlrev_b32_e32 v8, 16, v191
	v_and_b32_e32 v9, 0xffff0000, v191
	v_pk_fma_f32 v[2:3], v[160:161], v[8:9], v[2:3]
	v_lshlrev_b32_e32 v8, 16, v181
	v_and_b32_e32 v9, 0xffff0000, v181
	v_pk_fma_f32 v[8:9], v[82:83], v[8:9], v[2:3]
	v_lshlrev_b32_e32 v3, 16, v180
	v_lshlrev_b32_e32 v2, 16, v190
	v_mov_b32_e32 v68, v162
	v_mov_b32_e32 v69, v140
	v_pk_mul_f32 v[2:3], v[68:69], v[2:3]
	v_and_b32_e32 v69, 0xffff0000, v180
	v_and_b32_e32 v68, 0xffff0000, v190
	v_mov_b32_e32 v140, v163
	v_mov_b32_e32 v70, v110
	v_mov_b32_e32 v71, v112
	v_pk_mul_f32 v[68:69], v[140:141], v[68:69]
	v_pk_add_f32 v[56:57], v[56:57], v[70:71]
	v_mov_b32_e32 v112, v111
	v_pk_add_f32 v[56:57], v[56:57], v[112:113]
	v_mov_b32_e32 v70, v2
	v_mov_b32_e32 v71, v68
	v_pk_add_f32 v[56:57], v[56:57], v[70:71]
	v_mov_b32_e32 v68, v3
	v_pk_add_f32 v[56:57], v[56:57], v[68:69]
	v_lshlrev_b32_e32 v3, 16, v145
	v_lshlrev_b32_e32 v2, 16, v189
	v_mov_b32_e32 v68, v164
	v_mov_b32_e32 v69, v142
	v_pk_mul_f32 v[2:3], v[68:69], v[2:3]
	v_and_b32_e32 v69, 0xffff0000, v145
	v_and_b32_e32 v68, 0xffff0000, v189
	v_mov_b32_e32 v142, v165
	v_mov_b32_e32 v70, v106
	v_mov_b32_e32 v71, v108
	v_pk_mul_f32 v[68:69], v[142:143], v[68:69]
	v_pk_add_f32 v[58:59], v[58:59], v[70:71]
	v_mov_b32_e32 v108, v107
	v_pk_add_f32 v[58:59], v[58:59], v[108:109]
	v_mov_b32_e32 v70, v2
	v_mov_b32_e32 v71, v68
	v_pk_add_f32 v[58:59], v[58:59], v[70:71]
	v_mov_b32_e32 v68, v3
	v_pk_add_f32 v[58:59], v[58:59], v[68:69]
	ds_read_b128 v[68:71], v138 offset:39296
	ds_read_b128 v[72:75], v138 offset:39312
	v_lshlrev_b32_e32 v2, 16, v198
	v_and_b32_e32 v3, 0xffff0000, v198
	v_pk_fma_f32 v[2:3], v[48:49], v[2:3], v[44:45]
	v_lshlrev_b32_e32 v44, 16, v4
	v_and_b32_e32 v45, 0xffff0000, v4
	v_pk_fma_f32 v[2:3], v[60:61], v[44:45], v[2:3]
	v_lshlrev_b32_e32 v44, 16, v188
	v_and_b32_e32 v45, 0xffff0000, v188
	v_pk_fma_f32 v[2:3], v[76:77], v[44:45], v[2:3]
	v_lshlrev_b32_e32 v44, 16, v139
	v_and_b32_e32 v45, 0xffff0000, v139
	s_waitcnt lgkmcnt(0)
; #define LAS __attribute__((address_space(3)))
; __device__ __forceinline__ unsigned cvt_pk_bf16(float lo, float hi) { unsigned r; asm volatile("v_cvt_pk_bf16_f32 %0, %1, %2" : "=v"(r) : "v"(lo), "v"(hi)); return r; }
; __device__ __forceinline__ float bf_lo(unsigned w) { return __uint_as_float(w << 16); }
; __device__ __forceinline__ float bf_hi(unsigned w) { return __uint_as_float(w & 0xffff0000u); }
; template <int PASS>
; __device__ __forceinline__ void lru_item(Frame& F, const LAS bf16* lw, const LAS float* prm, const LAS float* cwl, LAS float* xs, LAS unsigned char* pf, int head, int item, int nitem) {
;     ...
; #pragma unroll
;     for (int k = 0; k < 4; ++k)
; #pragma unroll
;         for (int ks = 0; ks < 4; ++ks) {
;             const u32x4 w = vw[k][ks]; const int ch = 16 * ks + 8 * hh;
;             const f32x4 c0 = *(const LAS f32x4*)(cwl + k * 64 + ch), c1 = *(const LAS f32x4*)(cwl + k * 64 + ch + 4);
;             xa[ks][0] += c0[0] * bf_lo(w.x); xa[ks][1] += c0[1] * bf_hi(w.x); xa[ks][2] += c0[2] * bf_lo(w.y); xa[ks][3] += c0[3] * bf_hi(w.y);
;             xa[ks][4] += c1[0] * bf_lo(w.z); xa[ks][5] += c1[1] * bf_hi(w.z); xa[ks][6] += c1[2] * bf_lo(w.w); xa[ks][7] += c1[3] * bf_hi(w.w);
;         }
;     bf16x8 af[4];
; #pragma unroll
;     for (int ks = 0; ks < 4; ++ks) {
;         u32x4 w; w.x = cvt_pk_bf16(xa[ks][0], xa[ks][1]); w.y = cvt_pk_bf16(xa[ks][2], xa[ks][3]); w.z = cvt_pk_bf16(xa[ks][4], xa[ks][5]); w.w = cvt_pk_bf16(xa[ks][6], xa[ks][7]);
;         af[ks] = __builtin_bit_cast(bf16x8, w);
;         *(LAS f32x4*)(xs + t * 68 + 16 * ks + 8 * hh) = (f32x4){xa[ks][0], xa[ks][1], xa[ks][2], xa[ks][3]};
;         *(LAS f32x4*)(xs + t * 68 + 16 * ks + 8 * hh + 4) = (f32x4){xa[ks][4], xa[ks][5], xa[ks][6], xa[ks][7]};
;     }
;     if (PASS == 2) {
; #pragma unroll
;         for (int ks = 0; ks < 4; ++ks) gq[ks] = *(const u32x4*)((const bf16*)(F.ws + WS_GG) + tok * LRUW + head * 64 + 16 * ks + 8 * hh);
;     }
	v_pk_fma_f32 v[2:3], v[68:69], v[44:45], v[2:3]
	v_lshlrev_b32_e32 v44, 16, v197
	v_and_b32_e32 v45, 0xffff0000, v197
	v_pk_fma_f32 v[44:45], v[50:51], v[44:45], v[46:47]
	v_lshlrev_b32_e32 v4, 16, v5
	v_and_b32_e32 v5, 0xffff0000, v5
	v_pk_fma_f32 v[4:5], v[62:63], v[4:5], v[44:45]
	v_lshlrev_b32_e32 v44, 16, v187
	v_and_b32_e32 v45, 0xffff0000, v187
	v_pk_fma_f32 v[4:5], v[78:79], v[44:45], v[4:5]
	v_lshlrev_b32_e32 v44, 16, v136
	v_and_b32_e32 v45, 0xffff0000, v136
	v_pk_fma_f32 v[4:5], v[70:71], v[44:45], v[4:5]
	v_lshlrev_b32_e32 v45, 16, v135
	v_lshlrev_b32_e32 v44, 16, v137
	v_mov_b32_e32 v46, v64
	v_mov_b32_e32 v47, v72
	v_pk_mul_f32 v[44:45], v[46:47], v[44:45]
	v_and_b32_e32 v47, 0xffff0000, v135
	v_and_b32_e32 v46, 0xffff0000, v137
	v_mov_b32_e32 v72, v65
	v_mov_b32_e32 v48, v102
	v_mov_b32_e32 v49, v104
	v_pk_mul_f32 v[46:47], v[72:73], v[46:47]
	v_pk_add_f32 v[28:29], v[28:29], v[48:49]
	v_mov_b32_e32 v104, v103
	v_pk_add_f32 v[28:29], v[28:29], v[104:105]
	v_mov_b32_e32 v48, v44
	v_mov_b32_e32 v49, v46
	v_pk_add_f32 v[28:29], v[28:29], v[48:49]
	v_mov_b32_e32 v46, v45
	v_pk_add_f32 v[28:29], v[28:29], v[46:47]
	v_lshlrev_b32_e32 v45, 16, v132
	v_lshlrev_b32_e32 v44, 16, v134
	v_mov_b32_e32 v46, v66
	v_mov_b32_e32 v47, v74
	v_pk_mul_f32 v[44:45], v[46:47], v[44:45]
	v_and_b32_e32 v47, 0xffff0000, v132
	v_and_b32_e32 v46, 0xffff0000, v134
	v_mov_b32_e32 v74, v67
	v_mov_b32_e32 v48, v98
	v_mov_b32_e32 v49, v100
	v_pk_mul_f32 v[46:47], v[74:75], v[46:47]
	v_pk_add_f32 v[30:31], v[30:31], v[48:49]
	v_mov_b32_e32 v100, v99
	v_pk_add_f32 v[30:31], v[30:31], v[100:101]
	v_mov_b32_e32 v48, v44
	v_mov_b32_e32 v49, v46
	v_pk_add_f32 v[30:31], v[30:31], v[48:49]
	v_mov_b32_e32 v46, v45
	v_pk_add_f32 v[30:31], v[30:31], v[46:47]
	ds_read_b128 v[44:47], v138 offset:39360
	ds_read_b128 v[48:51], v138 offset:39376
	v_lshlrev_b32_e32 v60, 16, v133
	v_and_b32_e32 v61, 0xffff0000, v133
	v_pk_fma_f32 v[16:17], v[20:21], v[60:61], v[16:17]
	v_lshlrev_b32_e32 v20, 16, v0
	v_and_b32_e32 v21, 0xffff0000, v0
	v_pk_fma_f32 v[16:17], v[40:41], v[20:21], v[16:17]
	v_lshlrev_b32_e32 v20, 16, v130
	v_and_b32_e32 v21, 0xffff0000, v130
	v_pk_fma_f32 v[16:17], v[52:53], v[20:21], v[16:17]
	v_lshlrev_b32_e32 v20, 16, v129
	v_and_b32_e32 v21, 0xffff0000, v129
	s_waitcnt lgkmcnt(0)
	v_pk_fma_f32 v[16:17], v[44:45], v[20:21], v[16:17]
	v_lshlrev_b32_e32 v20, 16, v131
	v_and_b32_e32 v21, 0xffff0000, v131
	v_pk_fma_f32 v[18:19], v[22:23], v[20:21], v[18:19]
	v_lshlrev_b32_e32 v0, 16, v1
	v_and_b32_e32 v1, 0xffff0000, v1
	v_pk_fma_f32 v[0:1], v[42:43], v[0:1], v[18:19]
	v_lshlrev_b32_e32 v18, 16, v128
	v_and_b32_e32 v19, 0xffff0000, v128
	v_pk_fma_f32 v[0:1], v[54:55], v[18:19], v[0:1]
	v_lshlrev_b32_e32 v18, 16, v125
	v_and_b32_e32 v19, 0xffff0000, v125
	v_pk_fma_f32 v[18:19], v[46:47], v[18:19], v[0:1]
	v_lshlrev_b32_e32 v1, 16, v124
	v_lshlrev_b32_e32 v0, 16, v126
	v_mov_b32_e32 v20, v36
	v_mov_b32_e32 v21, v48
	v_pk_mul_f32 v[0:1], v[20:21], v[0:1]
	v_and_b32_e32 v21, 0xffff0000, v124
	v_and_b32_e32 v20, 0xffff0000, v126
	v_mov_b32_e32 v48, v37
	v_mov_b32_e32 v22, v94
	v_mov_b32_e32 v23, v96
	v_pk_mul_f32 v[20:21], v[48:49], v[20:21]
	v_pk_add_f32 v[12:13], v[12:13], v[22:23]
	v_mov_b32_e32 v96, v95
	v_pk_add_f32 v[12:13], v[12:13], v[96:97]
	v_mov_b32_e32 v22, v0
	v_mov_b32_e32 v23, v20
	v_pk_add_f32 v[12:13], v[12:13], v[22:23]
	v_mov_b32_e32 v20, v1
	v_pk_add_f32 v[12:13], v[12:13], v[20:21]
	v_lshlrev_b32_e32 v1, 16, v122
	v_lshlrev_b32_e32 v0, 16, v123
	v_mov_b32_e32 v20, v38
	v_mov_b32_e32 v21, v50
	v_mov_b32_e32 v22, v10
	v_mov_b32_e32 v23, v92
	v_pk_mul_f32 v[0:1], v[20:21], v[0:1]
	v_and_b32_e32 v21, 0xffff0000, v122
	v_and_b32_e32 v20, 0xffff0000, v123
	v_mov_b32_e32 v50, v39
	v_pk_add_f32 v[14:15], v[14:15], v[22:23]
	v_mov_b32_e32 v92, v11
	v_pk_mul_f32 v[20:21], v[50:51], v[20:21]
	v_pk_add_f32 v[10:11], v[14:15], v[92:93]
	v_mov_b32_e32 v14, v0
	v_mov_b32_e32 v0, s44
	v_mov_b32_e32 v15, v20
	v_mad_u32_u24 v108, v121, s55, v0
	v_mov_b32_e32 v91, v89
	v_pk_add_f32 v[10:11], v[10:11], v[14:15]
	v_mov_b32_e32 v20, v1
	v_add_u32_e32 v0, v108, v127
	v_pk_add_f32 v[14:15], v[10:11], v[20:21]
	v_cvt_pk_bf16_f32 v48, v32, v33
	v_cvt_pk_bf16_f32 v49, v34, v35
	v_cvt_pk_bf16_f32 v50, v24, v25
	v_cvt_pk_bf16_f32 v51, v26, v27
	ds_write_b128 v0, v[32:35] offset:40960
	ds_write_b128 v0, v[24:27] offset:40976
	v_cvt_pk_bf16_f32 v52, v6, v7
	v_cvt_pk_bf16_f32 v53, v8, v9
	v_cvt_pk_bf16_f32 v54, v56, v57
	v_cvt_pk_bf16_f32 v55, v58, v59
	ds_write_b128 v0, v[6:9] offset:41024
	ds_write_b128 v0, v[56:59] offset:41040
	v_cvt_pk_bf16_f32 v56, v2, v3
	v_cvt_pk_bf16_f32 v57, v4, v5
	v_cvt_pk_bf16_f32 v58, v28, v29
	v_cvt_pk_bf16_f32 v59, v30, v31
	ds_write_b128 v0, v[2:5] offset:41088
	ds_write_b128 v0, v[28:31] offset:41104
	v_cvt_pk_bf16_f32 v60, v16, v17
	v_cvt_pk_bf16_f32 v61, v18, v19
	v_cvt_pk_bf16_f32 v62, v12, v13
	v_cvt_pk_bf16_f32 v63, v14, v15
	ds_write_b128 v0, v[16:19] offset:41152
	ds_write_b128 v0, v[12:15] offset:41168
	v_lshl_add_u64 v[0:1], s[16:17], 0, v[90:91]
	v_lshlrev_b32_e32 v2, 3, v116
	v_lshlrev_b64 v[66:67], 11, v[0:1]
	v_ashrrev_i32_e32 v3, 31, v2
	v_lshl_add_u64 v[0:1], s[8:9], 0, v[66:67]
	v_lshlrev_b64 v[64:65], 1, v[2:3]
	v_lshl_add_u64 v[0:1], v[0:1], 0, v[64:65]
	global_load_dwordx4 v[44:47], v[0:1], off
	global_load_dwordx4 v[40:43], v[0:1], off offset:32
	global_load_dwordx4 v[36:39], v[0:1], off offset:64
	global_load_dwordx4 v[32:35], v[0:1], off offset:96
	s_waitcnt lgkmcnt(0)
	v_lshlrev_b32_e32 v0, 4, v116
	v_mul_u32_u24_e32 v1, 0x90, v121
	v_add3_u32 v148, 0, v0, v1
	ds_read_b128 v[0:3], v148
	ds_read_b128 v[16:19], v148 offset:32
	s_waitcnt lgkmcnt(0)
; #define LAS __attribute__((address_space(3)))
; template <int PASS>
; __device__ __forceinline__ void lru_item(Frame& F, const LAS bf16* lw, const LAS float* prm, const LAS float* cwl, LAS float* xs, LAS unsigned char* pf, int head, int item, int nitem) {
;     ...
;     float xd[2][16];
; #pragma unroll
;     for (int ct = 0; ct < 2; ++ct)
; #pragma unroll
;         for (int rg = 0; rg < 16; ++rg) xd[ct][rg] = xs[((rg & 3) + 8 * (rg >> 2) + 4 * hh) * 68 + t + 32 * ct];
;     float ysum[2][16];
; #pragma unroll
;     for (int d = 0; d < 2; ++d) {
; #pragma unroll
;         for (int ct = 0; ct < 2; ++ct) {
;             f32x16 acc[2];
; #pragma unroll
;             for (int gt = 0; gt < 2; ++gt) {
;                 f32x16 a; for (int i = 0; i < 16; ++i) a[i] = 0.f;
;                 const LAS bf16* wb = lw + ((d * 2 + gt) * 64 + t + 32 * ct) * LRU_WROW + 8 * hh;
; #pragma unroll
;                 for (int ks = 0; ks < 4; ++ks) a = __builtin_amdgcn_mfma_f32_32x32x16_bf16(af[ks], *(const LAS bf16x8*)(wb + 16 * ks), a, 0, 0, 0);
;                 acc[gt] = a;
;             }
;             const int chl = t + 32 * ct, ch = head * 64 + chl;
;             float av[16], bv[16];
;             {
;                 const float br = prm[(d * 3 + 0) * 64 + chl], bi = prm[(d * 3 + 1) * 64 + chl], c8 = prm[(d * 3 + 2) * 64 + chl];
; #pragma unroll
;                 for (int rg = 0; rg < 16; ++rg) {
;                     const float rr = __builtin_amdgcn_rcpf(1.f + __builtin_amdgcn_exp2f(acc[0][rg] + br)), ei = 1.f + __builtin_amdgcn_exp2f(acc[1][rg] + bi);
;                     const float a = __builtin_amdgcn_exp2f(c8 * rr), om = fmaxf(fmaf(-a, a, 1.f), 1e-30f);
;                     av[rg] = a; bv[rg] = (om * __builtin_amdgcn_rsqf(om * ei * ei)) * xd[ct][rg];
	v_mfma_f32_32x32x16_bf16 v[0:15], v[48:51], v[0:3], 0
	v_mul_i32_i24_e32 v20, 0xfffffef4, v121
	v_mul_lo_u32 v21, v116, s61
	v_add3_u32 v96, v108, v20, v21
	ds_read_b128 v[20:23], v148 offset:96
	v_add_u32_e32 v109, 0xa000, v96
	v_add_u32_e32 v110, 0xa800, v96
	v_add_u32_e32 v112, 0xaa00, v96
	v_mfma_f32_32x32x16_bf16 v[0:15], v[52:55], v[16:19], v[0:15]
	ds_read_b128 v[16:19], v148 offset:64
	ds_read2_b32 v[76:77], v109 offset1:32
	ds_read2_b32 v[84:85], v109 offset0:68 offset1:100
	ds_read2_b32 v[90:91], v109 offset0:136 offset1:168
	ds_read2_b32 v[94:95], v109 offset0:204 offset1:236
	ds_read2_b32 v[70:71], v110 offset0:32 offset1:64
	v_add_u32_e32 v111, 0xb000, v96
	v_add_u32_e32 v217, 0, v88
	v_add_u32_e32 v113, 0xb400, v96
	v_add_u32_e32 v121, 0xb800, v96
	s_waitcnt lgkmcnt(0)
	v_mfma_f32_32x32x16_bf16 v[0:15], v[56:59], v[16:19], v[0:15]
	ds_read2_b32 v[78:79], v110 offset0:100 offset1:132
	ds_read2_b32 v[86:87], v110 offset0:168 offset1:200
	ds_read_b128 v[16:19], v148 offset:9216
	ds_read_b128 v[102:105], v148 offset:9248
	ds_read2_b32 v[100:101], v112 offset0:108 offset1:140
	ds_read2_b32 v[72:73], v111 offset0:64 offset1:96
	ds_read2_b32 v[74:75], v111 offset0:132 offset1:164
	ds_read2_b32 v[80:81], v111 offset0:200 offset1:232
	ds_read_b128 v[122:125], v148 offset:9280
	v_add_u32_e32 v215, 0x9000, v217
	ds_read2_b32 v[98:99], v113 offset0:12 offset1:44
	v_mfma_f32_32x32x16_bf16 v[0:15], v[60:63], v[20:23], v[0:15]
	ds_read2_b32 v[68:69], v121 offset0:96 offset1:128
	v_add_u32_e32 v88, 0xba00, v96
	v_cmp_gt_u32_e32 vcc, 32, v144
	s_waitcnt lgkmcnt(0)
	v_mfma_f32_32x32x16_bf16 v[16:31], v[48:51], v[16:19], 0
	v_mfma_f32_32x32x16_bf16 v[16:31], v[52:55], v[102:105], v[16:31]
	ds_read2_b32 v[104:105], v215 offset1:32
	ds_read2_b32 v[82:83], v121 offset0:164 offset1:196
	ds_read_b128 v[126:129], v148 offset:9312
	ds_read2_b32 v[92:93], v88 offset0:104 offset1:136
	ds_read2_b32 v[102:103], v215 offset0:64 offset1:96
	ds_read2_b32 v[106:107], v215 offset0:128 offset1:160
	ds_read_b128 v[166:169], v148 offset:13856
	s_waitcnt lgkmcnt(0)
	v_add_f32_e32 v4, v4, v104
	v_exp_f32_e32 v4, v4
	v_add_f32_e32 v5, v5, v104
	v_mfma_f32_32x32x16_bf16 v[16:31], v[56:59], v[122:125], v[16:31]
	v_exp_f32_e32 v5, v5
	v_add_f32_e32 v4, 1.0, v4
	v_rcp_f32_e32 v4, v4
	v_add_f32_e32 v6, v6, v104
	v_exp_f32_e32 v6, v6
	v_add_f32_e32 v5, 1.0, v5
	v_mul_f32_e32 v4, v106, v4
	v_mfma_f32_32x32x16_bf16 v[16:31], v[60:63], v[126:129], v[16:31]
	v_exp_f32_e32 v123, v4
	v_rcp_f32_e32 v5, v5
	v_add_f32_e32 v6, 1.0, v6
	v_rcp_f32_e32 v6, v6
	v_add_f32_e32 v7, v7, v104
	v_mul_f32_e32 v5, v106, v5
	v_exp_f32_e32 v5, v5
	s_nop 4
	v_add_f32_e32 v20, v20, v102
	v_exp_f32_e32 v20, v20
	v_mul_f32_e32 v6, v106, v6
	v_add_f32_e32 v22, v22, v102
	v_exp_f32_e32 v141, v6
	v_add_f32_e32 v4, 1.0, v20
	v_fma_f32 v20, -v123, v123, 1.0
	v_max_f32_e32 v20, 0xda24260, v20
	v_mul_f32_e32 v124, v4, v20
	v_mul_f32_e32 v4, v4, v124
	v_rsq_f32_e32 v4, v4
	v_lshlrev_b32_e32 v124, 2, v144
	v_xor_b32_e32 v128, 0x80, v124
	v_exp_f32_e32 v22, v22
	v_mul_f32_e32 v4, v20, v4
	v_mul_f32_e32 v124, v70, v4
	v_add_f32_e32 v4, v21, v102
	v_exp_f32_e32 v4, v4
	v_fma_f32 v20, -v5, v5, 1.0
	v_max_f32_e32 v20, 0xda24260, v20
	v_exp_f32_e32 v7, v7
	v_add_f32_e32 v4, 1.0, v4
	v_mul_f32_e32 v21, v4, v20
	v_mul_f32_e32 v4, v4, v21
	v_fma_f32 v21, -v141, v141, 1.0
	v_add_f32_e32 v6, 1.0, v22
	v_max_f32_e32 v21, 0xda24260, v21
	v_mul_f32_e32 v22, v6, v21
	v_add_f32_e32 v7, 1.0, v7
	v_mul_f32_e32 v6, v6, v22
	v_rcp_f32_e32 v7, v7
	v_rsq_f32_e32 v6, v6
	v_rsq_f32_e32 v4, v4
	v_add_f32_e32 v9, v9, v104
	v_mul_f32_e32 v7, v106, v7
	v_mul_f32_e32 v6, v21, v6
	v_exp_f32_e32 v21, v7
	v_add_f32_e32 v7, v8, v104
	v_exp_f32_e32 v7, v7
	v_mul_f32_e32 v4, v20, v4
	v_add_f32_e32 v20, v23, v102
	v_exp_f32_e32 v20, v20
	v_add_f32_e32 v7, 1.0, v7
	v_rcp_f32_e32 v7, v7
	v_add_f32_e32 v23, v24, v102
	v_add_f32_e32 v8, 1.0, v20
	v_fma_f32 v20, -v21, v21, 1.0
	v_mul_f32_e32 v7, v106, v7
	v_exp_f32_e32 v125, v7
	v_exp_f32_e32 v23, v23
	v_exp_f32_e32 v9, v9
	v_max_f32_e32 v20, 0xda24260, v20
	v_mul_f32_e32 v22, v8, v20
	v_mul_f32_e32 v7, v8, v22
	v_fma_f32 v22, -v125, v125, 1.0
	v_add_f32_e32 v8, 1.0, v23
	v_max_f32_e32 v22, 0xda24260, v22
	v_add_f32_e32 v9, 1.0, v9
	v_mul_f32_e32 v23, v8, v22
	v_rcp_f32_e32 v9, v9
	v_mul_f32_e32 v8, v8, v23
	v_rsq_f32_e32 v7, v7
	v_rsq_f32_e32 v8, v8
	v_add_f32_e32 v10, v10, v104
	v_exp_f32_e32 v10, v10
	v_mul_f32_e32 v9, v106, v9
	v_add_f32_e32 v23, v25, v102
	v_exp_f32_e32 v24, v9
	v_exp_f32_e32 v23, v23
	v_mul_f32_e32 v20, v20, v7
	v_mul_f32_e32 v7, v22, v8
	v_mul_f32_e32 v126, v72, v7
	v_add_f32_e32 v7, 1.0, v10
	v_rcp_f32_e32 v7, v7
	v_fma_f32 v9, -v24, v24, 1.0
	v_add_f32_e32 v8, 1.0, v23
	v_max_f32_e32 v9, 0xda24260, v9
	v_mul_f32_e32 v22, v8, v9
	v_mul_f32_e32 v8, v8, v22
	v_mul_f32_e32 v7, v106, v7
	v_rsq_f32_e32 v8, v8
	v_exp_f32_e32 v23, v7
	v_add_f32_e32 v7, v11, v104
	v_exp_f32_e32 v7, v7
	v_mul_f32_e32 v22, v9, v8
	v_add_f32_e32 v8, v26, v102
	v_exp_f32_e32 v8, v8
	v_add_f32_e32 v7, 1.0, v7
	v_rcp_f32_e32 v7, v7
	v_fma_f32 v9, -v23, v23, 1.0
	v_add_f32_e32 v8, 1.0, v8
	v_max_f32_e32 v9, 0xda24260, v9
	v_mul_f32_e32 v10, v8, v9
	v_mul_f32_e32 v7, v106, v7
	v_exp_f32_e32 v25, v7
	v_mul_f32_e32 v7, v8, v10
	v_rsq_f32_e32 v7, v7
	v_add_f32_e32 v11, v27, v102
	v_exp_f32_e32 v11, v11
	v_fma_f32 v10, -v25, v25, 1.0
	v_mul_f32_e32 v26, v9, v7
	v_add_f32_e32 v9, v13, v104
	v_exp_f32_e32 v9, v9
	v_add_f32_e32 v8, 1.0, v11
	v_add_f32_e32 v11, v12, v104
	v_exp_f32_e32 v11, v11
	v_add_f32_e32 v9, 1.0, v9
	v_rcp_f32_e32 v9, v9
	v_max_f32_e32 v10, 0xda24260, v10
	v_add_f32_e32 v11, 1.0, v11
; __device__ __forceinline__ float shx(float v, int o, int lane) { return __int_as_float(__builtin_amdgcn_ds_bpermute((lane ^ o) << 2, __float_as_int(v))); }
; __device__ __forceinline__ int shx(int v, int o, int lane) { return __builtin_amdgcn_ds_bpermute((lane ^ o) << 2, v); }
; template <int PASS>
; __device__ __forceinline__ void lru_item(Frame& F, const LAS bf16* lw, const LAS float* prm, const LAS float* cwl, LAS float* xs, LAS unsigned char* pf, int head, int item, int nitem) {
;     ...
;                     const float rr = __builtin_amdgcn_rcpf(1.f + __builtin_amdgcn_exp2f(acc[0][rg] + br)), ei = 1.f + __builtin_amdgcn_exp2f(acc[1][rg] + bi);
;                     const float a = __builtin_amdgcn_exp2f(c8 * rr), om = fmaxf(fmaf(-a, a, 1.f), 1e-30f);
;                     av[rg] = a; bv[rg] = (om * __builtin_amdgcn_rsqf(om * ei * ei)) * xd[ct][rg];
;                 }
;             }
;             float hl[16], cp[16], sA[4], sB[4];
; #pragma unroll
;             for (int q4 = 0; q4 < 4; ++q4) {
;                 if (d == 0) {
;                     hl[4 * q4] = bv[4 * q4]; cp[4 * q4] = av[4 * q4];
; #pragma unroll
;                     for (int i = 1; i < 4; ++i) { hl[4 * q4 + i] = av[4 * q4 + i] * hl[4 * q4 + i - 1] + bv[4 * q4 + i]; cp[4 * q4 + i] = av[4 * q4 + i] * cp[4 * q4 + i - 1]; }
;                     sA[q4] = cp[4 * q4 + 3]; sB[q4] = hl[4 * q4 + 3];
;                 } else {
;                     hl[4 * q4 + 3] = bv[4 * q4 + 3]; cp[4 * q4 + 3] = av[4 * q4 + 3];
; #pragma unroll
;                     for (int i = 2; i >= 0; --i) { hl[4 * q4 + i] = av[4 * q4 + i] * hl[4 * q4 + i + 1] + bv[4 * q4 + i]; cp[4 * q4 + i] = av[4 * q4 + i] * cp[4 * q4 + i + 1]; }
;                     sA[q4] = cp[4 * q4]; sB[q4] = hl[4 * q4];
;                 }
;             }
;             float Ae[4], Be[4], Ao[4], Bo[4];
; #pragma unroll
;             for (int q4 = 0; q4 < 4; ++q4) {
;                 const float oA = shx(sA[q4], 32, lane), oB = shx(sB[q4], 32, lane);
;                 Ae[q4] = hh ? oA : sA[q4]; Be[q4] = hh ? oB : sB[q4]; Ao[q4] = hh ? sA[q4] : oA; Bo[q4] = hh ? sB[q4] : oB;
	v_rcp_f32_e32 v11, v11
	v_mul_f32_e32 v12, v8, v10
	v_mul_f32_e32 v9, v106, v9
	v_mul_f32_e32 v8, v8, v12
	v_add_f32_e32 v12, v28, v102
	v_exp_f32_e32 v28, v9
	v_add_f32_e32 v9, v14, v104
	v_exp_f32_e32 v9, v9
	v_mul_f32_e32 v11, v106, v11
	v_rsq_f32_e32 v8, v8
	v_exp_f32_e32 v127, v11
	v_exp_f32_e32 v12, v12
	v_add_f32_e32 v9, 1.0, v9
	v_rcp_f32_e32 v9, v9
	v_mul_f32_e32 v27, v10, v8
	v_fma_f32 v8, -v127, v127, 1.0
	v_add_f32_e32 v7, 1.0, v12
	v_max_f32_e32 v8, 0xda24260, v8
	v_mul_f32_e32 v10, v7, v8
	v_mul_f32_e32 v7, v7, v10
	v_mul_f32_e32 v9, v106, v9
	v_rsq_f32_e32 v7, v7
	v_add_f32_e32 v10, v29, v102
	v_exp_f32_e32 v29, v9
	v_add_f32_e32 v9, v15, v104
	v_exp_f32_e32 v10, v10
	v_exp_f32_e32 v9, v9
	v_add_f32_e32 v3, v3, v104
	v_exp_f32_e32 v3, v3
	v_mul_f32_e32 v7, v8, v7
	v_fma_f32 v8, -v28, v28, 1.0
	v_mul_f32_e32 v129, v68, v7
	v_add_f32_e32 v7, 1.0, v10
	v_max_f32_e32 v8, 0xda24260, v8
	v_add_f32_e32 v9, 1.0, v9
	v_mul_f32_e32 v10, v7, v8
	v_rcp_f32_e32 v9, v9
	v_mul_f32_e32 v7, v7, v10
	v_add_f32_e32 v10, v30, v102
	v_add_f32_e32 v3, 1.0, v3
	v_exp_f32_e32 v10, v10
	v_rcp_f32_e32 v3, v3
	v_rsq_f32_e32 v7, v7
	v_add_f32_e32 v2, v2, v104
	v_mul_f32_e32 v9, v106, v9
	v_exp_f32_e32 v2, v2
	v_fma_f32 v11, -v29, v29, 1.0
	v_add_f32_e32 v13, v31, v102
	v_exp_f32_e32 v30, v9
	v_add_f32_e32 v10, 1.0, v10
	v_max_f32_e32 v11, 0xda24260, v11
	v_exp_f32_e32 v13, v13
	v_mul_f32_e32 v3, v106, v3
	v_add_f32_e32 v1, v1, v104
	v_mul_f32_e32 v12, v10, v11
	v_mul_f32_e32 v31, v8, v7
	v_exp_f32_e32 v3, v3
	v_add_f32_e32 v7, v19, v102
	v_exp_f32_e32 v1, v1
	v_mul_f32_e32 v9, v10, v12
	v_exp_f32_e32 v7, v7
	v_add_f32_e32 v2, 1.0, v2
	v_rsq_f32_e32 v9, v9
	v_fma_f32 v12, -v30, v30, 1.0
	v_rcp_f32_e32 v2, v2
	v_add_f32_e32 v0, v0, v104
	v_add_f32_e32 v10, 1.0, v13
	v_max_f32_e32 v12, 0xda24260, v12
	v_exp_f32_e32 v0, v0
	v_mul_f32_e32 v13, v10, v12
	v_fma_f32 v8, -v3, v3, 1.0
	v_add_f32_e32 v1, 1.0, v1
	v_mul_f32_e32 v10, v10, v13
	v_max_f32_e32 v8, 0xda24260, v8
	v_add_f32_e32 v7, 1.0, v7
	v_rcp_f32_e32 v1, v1
	v_rsq_f32_e32 v10, v10
	v_mul_f32_e32 v152, v11, v9
	v_mul_f32_e32 v9, v7, v8
	v_mul_f32_e32 v2, v106, v2
	v_mul_f32_e32 v7, v7, v9
	v_exp_f32_e32 v2, v2
	v_add_f32_e32 v9, v18, v102
	v_add_f32_e32 v0, 1.0, v0
	v_exp_f32_e32 v9, v9
	v_rcp_f32_e32 v0, v0
	v_mul_f32_e32 v1, v106, v1
	v_mul_f32_e32 v153, v12, v10
	v_exp_f32_e32 v1, v1
	v_add_f32_e32 v12, v17, v102
	v_fma_f32 v10, -v2, v2, 1.0
	v_exp_f32_e32 v12, v12
	v_max_f32_e32 v10, 0xda24260, v10
	v_add_f32_e32 v9, 1.0, v9
	v_mul_f32_e32 v0, v106, v0
	v_mul_f32_e32 v11, v9, v10
	v_exp_f32_e32 v130, v0
	v_add_f32_e32 v0, v16, v102
	v_mul_f32_e32 v9, v9, v11
	v_fma_f32 v11, -v1, v1, 1.0
	v_exp_f32_e32 v0, v0
	v_max_f32_e32 v11, 0xda24260, v11
	v_add_f32_e32 v12, 1.0, v12
	v_mul_f32_e32 v13, v12, v11
	v_mul_f32_e32 v12, v12, v13
	v_fma_f32 v13, -v130, v130, 1.0
	v_max_f32_e32 v13, 0xda24260, v13
	v_add_f32_e32 v0, 1.0, v0
	v_mul_f32_e32 v14, v0, v13
	v_mul_f32_e32 v0, v0, v14
	v_rsq_f32_e32 v0, v0
	v_rsq_f32_e32 v7, v7
	v_rsq_f32_e32 v9, v9
	v_rsq_f32_e32 v12, v12
	v_mul_f32_e32 v0, v13, v0
	v_mul_f32_e32 v131, v76, v0
	v_mul_f32_e32 v7, v8, v7
	v_mul_f32_e32 v8, v10, v9
	v_mul_f32_e32 v9, v11, v12
	v_mul_f32_e32 v132, v1, v131
	v_fmac_f32_e32 v132, v84, v9
	v_mul_f32_e32 v133, v130, v1
	v_mul_f32_e32 v134, v2, v132
	v_fmac_f32_e32 v134, v90, v8
	v_mul_f32_e32 v135, v2, v133
	v_mul_f32_e32 v136, v3, v134
	v_mul_f32_e32 v137, v3, v135
	ds_read_b128 v[0:3], v148 offset:4608
	ds_read_b128 v[16:19], v148 offset:4640
	v_mul_f32_e32 v138, v5, v124
	v_fmac_f32_e32 v138, v78, v4
	v_mul_f32_e32 v140, v141, v138
	v_fmac_f32_e32 v136, v94, v7
	v_mul_f32_e32 v139, v123, v5
	v_fmac_f32_e32 v140, v86, v6
	s_waitcnt lgkmcnt(0)
	v_mfma_f32_32x32x16_bf16 v[0:15], v[48:51], v[0:3], 0
	v_mul_f32_e32 v145, v24, v126
	v_mul_f32_e32 v141, v141, v139
	v_mul_f32_e32 v142, v21, v140
	v_fmac_f32_e32 v145, v74, v22
	v_mul_f32_e32 v146, v125, v24
	v_fmac_f32_e32 v142, v100, v20
	v_mul_f32_e32 v143, v21, v141
	v_mfma_f32_32x32x16_bf16 v[0:15], v[52:55], v[16:19], v[0:15]
	ds_read_b128 v[16:19], v148 offset:4672
	v_mul_f32_e32 v147, v23, v145
	v_mul_f32_e32 v149, v23, v146
	ds_read_b128 v[20:23], v148 offset:4704
	v_mul_f32_e32 v154, v28, v129
	v_fmac_f32_e32 v154, v82, v31
	v_fmac_f32_e32 v147, v80, v26
	s_waitcnt lgkmcnt(0)
	v_mfma_f32_32x32x16_bf16 v[0:15], v[56:59], v[16:19], v[0:15]
	ds_read_b128 v[16:19], v148 offset:13824
	v_mul_f32_e32 v155, v127, v28
	v_mul_f32_e32 v156, v29, v154
	v_mul_f32_e32 v150, v25, v147
	v_fmac_f32_e32 v156, v92, v152
	v_mul_f32_e32 v157, v29, v155
	v_fmac_f32_e32 v150, v98, v27
	v_mul_f32_e32 v151, v25, v149
	v_mfma_f32_32x32x16_bf16 v[0:15], v[60:63], v[20:23], v[0:15]
	v_mul_f32_e32 v159, v30, v156
	v_mul_f32_e32 v160, v30, v157
	ds_read_b128 v[170:173], v148 offset:13920
	ds_bpermute_b32 v102, v128, v137
	ds_bpermute_b32 v104, v128, v136
	v_add_u32_e32 v122, 0xbc00, v96
	ds_read2_b32 v[96:97], v122 offset0:44 offset1:76
	s_waitcnt lgkmcnt(0)
	v_mfma_f32_32x32x16_bf16 v[16:31], v[48:51], v[16:19], 0
	s_nop 2
	v_add_f32_e32 v4, v4, v105
	v_exp_f32_e32 v4, v4
	v_cndmask_b32_e32 v162, v102, v137, vcc
	v_cndmask_b32_e32 v163, v137, v102, vcc
	ds_bpermute_b32 v102, v128, v151
	v_add_f32_e32 v4, 1.0, v4
	v_rcp_f32_e32 v4, v4
	v_mfma_f32_32x32x16_bf16 v[16:31], v[52:55], v[166:169], v[16:31]
	ds_read_b128 v[166:169], v148 offset:13888
	v_cndmask_b32_e32 v144, v104, v136, vcc
	v_mul_f32_e32 v4, v107, v4
	v_cndmask_b32_e32 v152, v136, v104, vcc
	ds_bpermute_b32 v104, v128, v150
	v_add_f32_e32 v5, v5, v105
	v_exp_f32_e32 v5, v5
	s_waitcnt lgkmcnt(0)
; __device__ __forceinline__ float shx(float v, int o, int lane) { return __int_as_float(__builtin_amdgcn_ds_bpermute((lane ^ o) << 2, __float_as_int(v))); }
; __device__ __forceinline__ int shx(int v, int o, int lane) { return __builtin_amdgcn_ds_bpermute((lane ^ o) << 2, v); }
; template <int PASS>
; __device__ __forceinline__ void lru_item(Frame& F, const LAS bf16* lw, const LAS float* prm, const LAS float* cwl, LAS float* xs, LAS unsigned char* pf, int head, int item, int nitem) {
;     ...
;             {
;                 const float br = prm[(d * 3 + 0) * 64 + chl], bi = prm[(d * 3 + 1) * 64 + chl], c8 = prm[(d * 3 + 2) * 64 + chl];
; #pragma unroll
;                 for (int rg = 0; rg < 16; ++rg) {
;                     const float rr = __builtin_amdgcn_rcpf(1.f + __builtin_amdgcn_exp2f(acc[0][rg] + br)), ei = 1.f + __builtin_amdgcn_exp2f(acc[1][rg] + bi);
;                     const float a = __builtin_amdgcn_exp2f(c8 * rr), om = fmaxf(fmaf(-a, a, 1.f), 1e-30f);
;                     av[rg] = a; bv[rg] = (om * __builtin_amdgcn_rsqf(om * ei * ei)) * xd[ct][rg];
;                 }
;             }
;             float hl[16], cp[16], sA[4], sB[4];
; #pragma unroll
;             for (int q4 = 0; q4 < 4; ++q4) {
;                 if (d == 0) {
;                     hl[4 * q4] = bv[4 * q4]; cp[4 * q4] = av[4 * q4];
; #pragma unroll
;                     for (int i = 1; i < 4; ++i) { hl[4 * q4 + i] = av[4 * q4 + i] * hl[4 * q4 + i - 1] + bv[4 * q4 + i]; cp[4 * q4 + i] = av[4 * q4 + i] * cp[4 * q4 + i - 1]; }
;                     sA[q4] = cp[4 * q4 + 3]; sB[q4] = hl[4 * q4 + 3];
;                 } else {
;                     hl[4 * q4 + 3] = bv[4 * q4 + 3]; cp[4 * q4 + 3] = av[4 * q4 + 3];
; #pragma unroll
;                     for (int i = 2; i >= 0; --i) { hl[4 * q4 + i] = av[4 * q4 + i] * hl[4 * q4 + i + 1] + bv[4 * q4 + i]; cp[4 * q4 + i] = av[4 * q4 + i] * cp[4 * q4 + i + 1]; }
;                     sA[q4] = cp[4 * q4]; sB[q4] = hl[4 * q4];
;                 }
;             }
;             float Ae[4], Be[4], Ao[4], Bo[4];
; #pragma unroll
;             for (int q4 = 0; q4 < 4; ++q4) {
;                 const float oA = shx(sA[q4], 32, lane), oB = shx(sB[q4], 32, lane);
;                 Ae[q4] = hh ? oA : sA[q4]; Be[q4] = hh ? oB : sB[q4]; Ao[q4] = hh ? sA[q4] : oA; Bo[q4] = hh ? sB[q4] : oB;
	v_mfma_f32_32x32x16_bf16 v[16:31], v[56:59], v[166:169], v[16:31]
	v_cndmask_b32_e32 v166, v102, v151, vcc
	v_cndmask_b32_e32 v167, v151, v102, vcc
	v_add_f32_e32 v6, v6, v105
	v_cndmask_b32_e32 v161, v104, v150, vcc
	v_cndmask_b32_e32 v168, v150, v104, vcc
	v_exp_f32_e32 v6, v6
	v_add_f32_e32 v5, 1.0, v5
	v_mfma_f32_32x32x16_bf16 v[16:31], v[60:63], v[170:173], v[16:31]
	v_exp_f32_e32 v171, v4
	ds_bpermute_b32 v4, v128, v160
	v_rcp_f32_e32 v5, v5
	v_add_f32_e32 v6, 1.0, v6
	v_fma_f32 v102, -v171, v171, 1.0
	v_max_f32_e32 v102, 0xda24260, v102
	v_rcp_f32_e32 v6, v6
	s_nop 4
	v_add_f32_e32 v20, v20, v103
	v_exp_f32_e32 v20, v20
	s_waitcnt lgkmcnt(0)
	v_cndmask_b32_e32 v170, v4, v160, vcc
	v_mul_f32_e32 v5, v107, v5
	v_exp_f32_e32 v5, v5
	v_add_f32_e32 v20, 1.0, v20
	v_mul_f32_e32 v104, v20, v102
	v_mul_f32_e32 v20, v20, v104
	v_rsq_f32_e32 v20, v20
	v_add_f32_e32 v22, v22, v103
	v_mul_f32_e32 v6, v107, v6
	v_exp_f32_e32 v22, v22
	v_mul_f32_e32 v4, v102, v20
	v_mul_f32_e32 v172, v71, v4
	v_add_f32_e32 v4, v21, v103
	v_exp_f32_e32 v4, v4
	v_exp_f32_e32 v6, v6
	v_fma_f32 v20, -v5, v5, 1.0
	v_add_f32_e32 v7, v7, v105
	v_add_f32_e32 v4, 1.0, v4
	v_max_f32_e32 v20, 0xda24260, v20
	v_exp_f32_e32 v7, v7
	v_mul_f32_e32 v21, v4, v20
	v_mul_f32_e32 v4, v4, v21
	v_add_f32_e32 v21, 1.0, v22
	v_fma_f32 v22, -v6, v6, 1.0
	v_add_f32_e32 v8, v8, v105
	v_max_f32_e32 v22, 0xda24260, v22
	v_exp_f32_e32 v8, v8
	v_mul_f32_e32 v102, v21, v22
	v_add_f32_e32 v7, 1.0, v7
	v_mul_f32_e32 v21, v21, v102
	v_rcp_f32_e32 v7, v7
	v_rsq_f32_e32 v4, v4
	v_rsq_f32_e32 v21, v21
	v_add_f32_e32 v8, 1.0, v8
	v_rcp_f32_e32 v8, v8
	v_mul_f32_e32 v7, v107, v7
	v_mul_f32_e32 v4, v20, v4
	v_mul_f32_e32 v20, v22, v21
	v_add_f32_e32 v21, v23, v103
	v_exp_f32_e32 v7, v7
	v_add_f32_e32 v9, v9, v105
	v_exp_f32_e32 v21, v21
	v_exp_f32_e32 v9, v9
	v_mul_f32_e32 v8, v107, v8
	v_add_f32_e32 v24, v24, v103
	v_exp_f32_e32 v173, v8
	v_fma_f32 v22, -v7, v7, 1.0
	v_exp_f32_e32 v24, v24
	v_add_f32_e32 v21, 1.0, v21
	v_max_f32_e32 v22, 0xda24260, v22
	v_add_f32_e32 v9, 1.0, v9
	v_mul_f32_e32 v23, v21, v22
	v_rcp_f32_e32 v9, v9
	v_mul_f32_e32 v8, v21, v23
	v_fma_f32 v23, -v173, v173, 1.0
	v_add_f32_e32 v21, 1.0, v24
	v_max_f32_e32 v23, 0xda24260, v23
	v_mul_f32_e32 v24, v21, v23
	v_mul_f32_e32 v21, v21, v24
	v_mul_f32_e32 v9, v107, v9
	v_rsq_f32_e32 v21, v21
	v_add_f32_e32 v24, v25, v103
	v_exp_f32_e32 v9, v9
	v_rsq_f32_e32 v8, v8
	v_exp_f32_e32 v24, v24
	v_add_f32_e32 v10, v10, v105
	v_exp_f32_e32 v10, v10
	v_mul_f32_e32 v21, v23, v21
	v_fma_f32 v23, -v9, v9, 1.0
	v_mul_f32_e32 v8, v22, v8
	v_add_f32_e32 v22, 1.0, v24
	v_max_f32_e32 v23, 0xda24260, v23
	v_mul_f32_e32 v24, v22, v23
	v_add_f32_e32 v10, 1.0, v10
	v_mul_f32_e32 v22, v22, v24
	v_rcp_f32_e32 v10, v10
	v_rsq_f32_e32 v22, v22
	v_mul_f32_e32 v174, v73, v21
	v_add_f32_e32 v12, v12, v105
	v_mul_f32_e32 v10, v107, v10
	v_mul_f32_e32 v21, v23, v22
	v_exp_f32_e32 v23, v10
	v_add_f32_e32 v10, v11, v105
	v_exp_f32_e32 v10, v10
	v_exp_f32_e32 v12, v12
	v_add_f32_e32 v22, v26, v103
	v_exp_f32_e32 v22, v22
	v_add_f32_e32 v10, 1.0, v10
	v_rcp_f32_e32 v10, v10
	v_add_f32_e32 v12, 1.0, v12
	v_rcp_f32_e32 v12, v12
	v_add_f32_e32 v25, v27, v103
	v_mul_f32_e32 v10, v107, v10
	v_exp_f32_e32 v26, v10
	v_mul_f32_e32 v12, v107, v12
	v_add_f32_e32 v11, 1.0, v22
	v_fma_f32 v22, -v23, v23, 1.0
	v_exp_f32_e32 v25, v25
	v_exp_f32_e32 v175, v12
	v_add_f32_e32 v12, v13, v105
	v_max_f32_e32 v22, 0xda24260, v22
	v_exp_f32_e32 v12, v12
	v_mul_f32_e32 v24, v11, v22
	v_mul_f32_e32 v10, v11, v24
	v_fma_f32 v24, -v26, v26, 1.0
	v_add_f32_e32 v11, 1.0, v25
	v_max_f32_e32 v24, 0xda24260, v24
	v_mul_f32_e32 v25, v11, v24
	v_add_f32_e32 v12, 1.0, v12
	v_mul_f32_e32 v11, v11, v25
	v_add_f32_e32 v25, v28, v103
	v_rcp_f32_e32 v12, v12
	v_rsq_f32_e32 v10, v10
	v_exp_f32_e32 v25, v25
	v_rsq_f32_e32 v11, v11
	v_mul_f32_e32 v12, v107, v12
	v_mul_f32_e32 v22, v22, v10
	v_add_f32_e32 v10, 1.0, v25
	v_exp_f32_e32 v25, v12
	v_add_f32_e32 v12, v14, v105
	v_exp_f32_e32 v12, v12
	v_mul_f32_e32 v24, v24, v11
	v_fma_f32 v11, -v175, v175, 1.0
	v_max_f32_e32 v11, 0xda24260, v11
	v_add_f32_e32 v12, 1.0, v12
	v_rcp_f32_e32 v12, v12
	v_mul_f32_e32 v13, v10, v11
	v_mul_f32_e32 v10, v10, v13
	v_rsq_f32_e32 v10, v10
	v_mul_f32_e32 v12, v107, v12
	v_exp_f32_e32 v27, v12
	v_add_f32_e32 v12, v15, v105
	v_add_f32_e32 v13, v29, v103
	v_exp_f32_e32 v12, v12
	v_exp_f32_e32 v13, v13
	v_mul_f32_e32 v10, v11, v10
	v_fma_f32 v11, -v25, v25, 1.0
	v_add_f32_e32 v12, 1.0, v12
	v_mul_f32_e32 v176, v69, v10
	v_add_f32_e32 v10, 1.0, v13
	v_max_f32_e32 v11, 0xda24260, v11
	v_rcp_f32_e32 v12, v12
	v_mul_f32_e32 v13, v10, v11
	v_add_f32_e32 v3, v3, v105
	v_mul_f32_e32 v10, v10, v13
	v_add_f32_e32 v13, v30, v103
	v_exp_f32_e32 v3, v3
	v_exp_f32_e32 v13, v13
	v_mul_f32_e32 v12, v107, v12
	v_add_f32_e32 v28, v31, v103
	v_exp_f32_e32 v29, v12
	v_fma_f32 v14, -v27, v27, 1.0
	v_exp_f32_e32 v28, v28
	v_add_f32_e32 v3, 1.0, v3
	v_add_f32_e32 v13, 1.0, v13
	v_max_f32_e32 v14, 0xda24260, v14
	v_rcp_f32_e32 v3, v3
	v_rsq_f32_e32 v10, v10
	v_mul_f32_e32 v15, v13, v14
	v_add_f32_e32 v2, v2, v105
	v_mul_f32_e32 v12, v13, v15
	v_fma_f32 v15, -v29, v29, 1.0
	v_exp_f32_e32 v2, v2
	v_add_f32_e32 v13, 1.0, v28
	v_max_f32_e32 v15, 0xda24260, v15
	v_mul_f32_e32 v28, v13, v15
	v_mul_f32_e32 v3, v107, v3
	v_add_f32_e32 v1, v1, v105
	v_mul_f32_e32 v13, v13, v28
	v_mul_f32_e32 v28, v11, v10
	v_exp_f32_e32 v3, v3
	v_add_f32_e32 v10, v19, v103
	v_exp_f32_e32 v1, v1
	v_add_f32_e32 v0, v0, v105
	v_exp_f32_e32 v10, v10
	v_add_f32_e32 v2, 1.0, v2
	v_exp_f32_e32 v0, v0
	v_rsq_f32_e32 v12, v12
	v_rcp_f32_e32 v2, v2
	v_fma_f32 v11, -v3, v3, 1.0
; template <int PASS>
; __device__ __forceinline__ void lru_item(Frame& F, const LAS bf16* lw, const LAS float* prm, const LAS float* cwl, LAS float* xs, LAS unsigned char* pf, int head, int item, int nitem) {
;     ...
;     for (int d = 0; d < 2; ++d) {
; #pragma unroll
;         for (int ct = 0; ct < 2; ++ct) {
;             f32x16 acc[2];
; #pragma unroll
;             for (int gt = 0; gt < 2; ++gt) {
;                 f32x16 a; for (int i = 0; i < 16; ++i) a[i] = 0.f;
;                 const LAS bf16* wb = lw + ((d * 2 + gt) * 64 + t + 32 * ct) * LRU_WROW + 8 * hh;
; #pragma unroll
;                 for (int ks = 0; ks < 4; ++ks) a = __builtin_amdgcn_mfma_f32_32x32x16_bf16(af[ks], *(const LAS bf16x8*)(wb + 16 * ks), a, 0, 0, 0);
;                 acc[gt] = a;
;             }
;             const int chl = t + 32 * ct, ch = head * 64 + chl;
;             float av[16], bv[16];
;             {
;                 const float br = prm[(d * 3 + 0) * 64 + chl], bi = prm[(d * 3 + 1) * 64 + chl], c8 = prm[(d * 3 + 2) * 64 + chl];
; #pragma unroll
;                 for (int rg = 0; rg < 16; ++rg) {
;                     const float rr = __builtin_amdgcn_rcpf(1.f + __builtin_amdgcn_exp2f(acc[0][rg] + br)), ei = 1.f + __builtin_amdgcn_exp2f(acc[1][rg] + bi);
;                     const float a = __builtin_amdgcn_exp2f(c8 * rr), om = fmaxf(fmaf(-a, a, 1.f), 1e-30f);
;                     av[rg] = a; bv[rg] = (om * __builtin_amdgcn_rsqf(om * ei * ei)) * xd[ct][rg];
;                 }
;             }
;             float hl[16], cp[16], sA[4], sB[4];
; #pragma unroll
;             for (int q4 = 0; q4 < 4; ++q4) {
;                 if (d == 0) {
;                     hl[4 * q4] = bv[4 * q4]; cp[4 * q4] = av[4 * q4];
; #pragma unroll
;                     for (int i = 1; i < 4; ++i) { hl[4 * q4 + i] = av[4 * q4 + i] * hl[4 * q4 + i - 1] + bv[4 * q4 + i]; cp[4 * q4 + i] = av[4 * q4 + i] * cp[4 * q4 + i - 1]; }
;                     sA[q4] = cp[4 * q4 + 3]; sB[q4] = hl[4 * q4 + 3];
;                 } else {
;                     hl[4 * q4 + 3] = bv[4 * q4 + 3]; cp[4 * q4 + 3] = av[4 * q4 + 3];
; #pragma unroll
;                     for (int i = 2; i >= 0; --i) { hl[4 * q4 + i] = av[4 * q4 + i] * hl[4 * q4 + i + 1] + bv[4 * q4 + i]; cp[4 * q4 + i] = av[4 * q4 + i] * cp[4 * q4 + i + 1]; }
;                     sA[q4] = cp[4 * q4]; sB[q4] = hl[4 * q4];
;                 }
	v_add_f32_e32 v1, 1.0, v1
	v_max_f32_e32 v11, 0xda24260, v11
	v_add_f32_e32 v10, 1.0, v10
	v_rcp_f32_e32 v1, v1
	v_add_f32_e32 v0, 1.0, v0
	v_rsq_f32_e32 v13, v13
	v_mul_f32_e32 v30, v14, v12
	v_mul_f32_e32 v12, v10, v11
	v_mul_f32_e32 v2, v107, v2
	v_rcp_f32_e32 v0, v0
	v_mul_f32_e32 v10, v10, v12
	v_exp_f32_e32 v2, v2
	v_add_f32_e32 v12, v18, v103
	v_exp_f32_e32 v12, v12
	v_mul_f32_e32 v1, v107, v1
	v_mul_f32_e32 v31, v15, v13
	v_exp_f32_e32 v1, v1
	v_add_f32_e32 v15, v17, v103
	v_mul_f32_e32 v0, v107, v0
	v_fma_f32 v13, -v2, v2, 1.0
	v_exp_f32_e32 v15, v15
	v_exp_f32_e32 v177, v0
	v_add_f32_e32 v0, v16, v103
	v_max_f32_e32 v13, 0xda24260, v13
	v_add_f32_e32 v12, 1.0, v12
	v_exp_f32_e32 v0, v0
	v_mul_f32_e32 v14, v12, v13
	v_mul_f32_e32 v12, v12, v14
	v_fma_f32 v14, -v1, v1, 1.0
	v_max_f32_e32 v14, 0xda24260, v14
	v_add_f32_e32 v15, 1.0, v15
	v_fma_f32 v16, -v177, v177, 1.0
	v_mul_f32_e32 v17, v15, v14
	v_max_f32_e32 v16, 0xda24260, v16
	v_add_f32_e32 v0, 1.0, v0
	v_mul_f32_e32 v15, v15, v17
	v_mul_f32_e32 v17, v0, v16
	v_mul_f32_e32 v0, v0, v17
	v_rsq_f32_e32 v0, v0
	v_rsq_f32_e32 v10, v10
	v_rsq_f32_e32 v12, v12
	v_rsq_f32_e32 v15, v15
	v_mul_f32_e32 v0, v16, v0
	v_mul_f32_e32 v178, v77, v0
	v_mul_f32_e32 v10, v11, v10
	v_mul_f32_e32 v11, v13, v12
	v_mul_f32_e32 v12, v14, v15
	v_mul_f32_e32 v179, v1, v178
	v_fmac_f32_e32 v179, v85, v12
	v_mul_f32_e32 v180, v177, v1
	v_mul_f32_e32 v181, v2, v179
	v_fmac_f32_e32 v181, v91, v11
	v_mul_f32_e32 v182, v2, v180
	v_mul_f32_e32 v183, v3, v181
	v_mul_f32_e32 v184, v3, v182
	v_mul_f32_e32 v185, v5, v172
	ds_read_b128 v[0:3], v148 offset:18432
	ds_read_b128 v[16:19], v148 offset:18464
	v_fmac_f32_e32 v185, v79, v4
	v_mul_f32_e32 v187, v6, v185
	v_mul_f32_e32 v186, v171, v5
	v_fmac_f32_e32 v187, v87, v20
	v_mul_f32_e32 v188, v6, v186
	v_mul_f32_e32 v189, v7, v187
	v_fmac_f32_e32 v183, v95, v10
	v_fmac_f32_e32 v189, v101, v8
	v_mul_f32_e32 v190, v7, v188
	v_mul_f32_e32 v191, v9, v174
	v_mul_f32_e32 v193, v173, v9
	s_waitcnt lgkmcnt(0)
	v_mfma_f32_32x32x16_bf16 v[0:15], v[48:51], v[0:3], 0
	v_fmac_f32_e32 v191, v75, v21
	v_mul_f32_e32 v194, v23, v191
	v_fmac_f32_e32 v194, v81, v22
	v_mul_f32_e32 v195, v23, v193
	ds_read_b128 v[20:23], v148 offset:18528
	v_mul_f32_e32 v196, v26, v194
	v_fmac_f32_e32 v196, v99, v24
	v_mfma_f32_32x32x16_bf16 v[0:15], v[52:55], v[16:19], v[0:15]
	ds_read_b128 v[16:19], v148 offset:18496
	v_mul_f32_e32 v200, v25, v176
	ds_bpermute_b32 v24, v128, v184
	v_fmac_f32_e32 v200, v83, v28
	v_mul_f32_e32 v202, v27, v200
	v_mul_f32_e32 v201, v175, v25
	v_fmac_f32_e32 v202, v93, v30
	s_waitcnt lgkmcnt(0)
	v_mfma_f32_32x32x16_bf16 v[0:15], v[56:59], v[16:19], v[0:15]
	ds_bpermute_b32 v16, v128, v183
	v_mul_f32_e32 v203, v27, v201
	v_mul_f32_e32 v206, v29, v202
	v_mul_f32_e32 v197, v26, v195
	v_fmac_f32_e32 v206, v97, v31
	s_waitcnt lgkmcnt(0)
	v_cndmask_b32_e32 v192, v16, v183, vcc
	v_cndmask_b32_e32 v198, v183, v16, vcc
	ds_read_b128 v[16:19], v148 offset:27648
	ds_read_b128 v[102:105], v148 offset:27680
	v_mul_f32_e32 v207, v29, v203
	v_cndmask_b32_e32 v208, v24, v184, vcc
	v_mfma_f32_32x32x16_bf16 v[0:15], v[60:63], v[20:23], v[0:15]
	v_cndmask_b32_e32 v209, v184, v24, vcc
	ds_bpermute_b32 v106, v128, v143
	ds_bpermute_b32 v107, v128, v189
	v_fmac_f32_e32 v159, v96, v153
	ds_bpermute_b32 v158, v128, v142
	ds_bpermute_b32 v169, v128, v159
	s_waitcnt lgkmcnt(0)
	v_cndmask_b32_e32 v164, v106, v143, vcc
	v_mfma_f32_32x32x16_bf16 v[16:31], v[48:51], v[16:19], 0
	v_cndmask_b32_e32 v165, v143, v106, vcc
	ds_bpermute_b32 v106, v128, v190
	v_cndmask_b32_e32 v199, v107, v189, vcc
	v_cndmask_b32_e32 v204, v189, v107, vcc
	ds_bpermute_b32 v213, v128, v197
	ds_bpermute_b32 v214, v128, v196
	s_waitcnt lgkmcnt(0)
	v_cndmask_b32_e32 v210, v106, v190, vcc
	v_mfma_f32_32x32x16_bf16 v[16:31], v[52:55], v[102:105], v[16:31]
	v_cndmask_b32_e32 v211, v190, v106, vcc
	ds_read_b128 v[102:105], v148 offset:27712
	ds_read2_b32 v[106:107], v215 offset0:192 offset1:224
	ds_read_b128 v[218:221], v148 offset:27744
	ds_bpermute_b32 v216, v128, v207
	ds_bpermute_b32 v215, v128, v206
	s_waitcnt vmcnt(4)
	v_fmac_f32_e32 v192, v119, v208
	s_waitcnt lgkmcnt(3)
	v_add_f32_e32 v4, v4, v106
	v_mfma_f32_32x32x16_bf16 v[16:31], v[56:59], v[102:105], v[16:31]
	v_exp_f32_e32 v4, v4
	v_add_u32_e32 v104, 0x9400, v217
	ds_read2_b32 v[102:103], v104 offset1:32
	ds_read2_b32 v[104:105], v104 offset0:64 offset1:96
	v_add_f32_e32 v6, v6, v106
	v_add_f32_e32 v4, 1.0, v4
	v_rcp_f32_e32 v4, v4
	v_exp_f32_e32 v6, v6
	s_waitcnt lgkmcnt(4)
	v_mfma_f32_32x32x16_bf16 v[16:31], v[60:63], v[218:221], v[16:31]
	v_add_f32_e32 v8, v8, v106
	s_waitcnt lgkmcnt(0)
; template <int PASS>
; __device__ __forceinline__ void lru_item(Frame& F, const LAS bf16* lw, const LAS float* prm, const LAS float* cwl, LAS float* xs, LAS unsigned char* pf, int head, int item, int nitem) {
;     ...
;             {
;                 const float br = prm[(d * 3 + 0) * 64 + chl], bi = prm[(d * 3 + 1) * 64 + chl], c8 = prm[(d * 3 + 2) * 64 + chl];
; #pragma unroll
;                 for (int rg = 0; rg < 16; ++rg) {
;                     const float rr = __builtin_amdgcn_rcpf(1.f + __builtin_amdgcn_exp2f(acc[0][rg] + br)), ei = 1.f + __builtin_amdgcn_exp2f(acc[1][rg] + bi);
;                     const float a = __builtin_amdgcn_exp2f(c8 * rr), om = fmaxf(fmaf(-a, a, 1.f), 1e-30f);
;                     av[rg] = a; bv[rg] = (om * __builtin_amdgcn_rsqf(om * ei * ei)) * xd[ct][rg];
;                 }
;             }
	v_mul_f32_e32 v4, v104, v4
	v_exp_f32_e32 v217, v4
	v_add_f32_e32 v4, v5, v106
	v_exp_f32_e32 v4, v4
	v_exp_f32_e32 v8, v8
	v_add_f32_e32 v9, v9, v106
	s_nop 3
	v_add_f32_e32 v20, v20, v102
	v_exp_f32_e32 v20, v20
	v_add_f32_e32 v4, 1.0, v4
	v_rcp_f32_e32 v4, v4
	v_add_f32_e32 v21, v21, v102
	v_add_f32_e32 v5, 1.0, v20
	v_fma_f32 v20, -v217, v217, 1.0
	v_max_f32_e32 v20, 0xda24260, v20
	v_mul_f32_e32 v218, v5, v20
	v_mul_f32_e32 v4, v104, v4
	v_exp_f32_e32 v222, v4
	v_mul_f32_e32 v4, v5, v218
	v_exp_f32_e32 v21, v21
	v_rsq_f32_e32 v4, v4
	v_add_f32_e32 v8, 1.0, v8
	v_rcp_f32_e32 v8, v8
	v_add_f32_e32 v5, 1.0, v21
	v_fma_f32 v21, -v222, v222, 1.0
	v_mul_f32_e32 v223, v20, v4
	v_add_f32_e32 v4, 1.0, v6
	v_add_f32_e32 v6, v7, v106
	v_max_f32_e32 v21, 0xda24260, v21
	v_exp_f32_e32 v6, v6
	v_mul_f32_e32 v218, v5, v21
	v_mul_f32_e32 v5, v5, v218
	v_rcp_f32_e32 v4, v4
	v_rsq_f32_e32 v5, v5
	v_add_f32_e32 v6, 1.0, v6
	v_rcp_f32_e32 v6, v6
	v_mul_f32_e32 v4, v104, v4
	v_mul_f32_e32 v224, v21, v5
	v_add_f32_e32 v5, v22, v102
	v_exp_f32_e32 v4, v4
	v_exp_f32_e32 v5, v5
	v_add_f32_e32 v20, v23, v102
	v_mul_f32_e32 v6, v104, v6
	v_exp_f32_e32 v22, v20
	v_exp_f32_e32 v20, v6
	v_fma_f32 v7, -v4, v4, 1.0
	v_add_f32_e32 v5, 1.0, v5
	v_max_f32_e32 v7, 0xda24260, v7
	v_mul_f32_e32 v21, v5, v7
	v_mul_f32_e32 v5, v5, v21
	v_fma_f32 v21, -v20, v20, 1.0
	v_add_f32_e32 v6, 1.0, v22
	v_max_f32_e32 v21, 0xda24260, v21
	v_mul_f32_e32 v22, v6, v21
	v_mul_f32_e32 v8, v104, v8
	v_mul_f32_e32 v6, v6, v22
	v_add_f32_e32 v22, v24, v102
	v_exp_f32_e32 v226, v8
	v_rsq_f32_e32 v5, v5
	v_exp_f32_e32 v22, v22
	v_rsq_f32_e32 v6, v6
	v_fma_f32 v8, -v226, v226, 1.0
	v_mul_f32_e32 v5, v7, v5
	v_add_f32_e32 v7, 1.0, v22
	v_max_f32_e32 v8, 0xda24260, v8
	v_mul_f32_e32 v6, v21, v6
	v_mul_f32_e32 v21, v7, v8
	v_mul_f32_e32 v7, v7, v21
	v_rsq_f32_e32 v7, v7
	v_exp_f32_e32 v9, v9
	v_add_f32_e32 v21, v25, v102
	v_exp_f32_e32 v22, v21
	v_mul_f32_e32 v227, v8, v7
	v_add_f32_e32 v8, v10, v106
	v_exp_f32_e32 v8, v8
	v_add_f32_e32 v9, 1.0, v9
	v_rcp_f32_e32 v9, v9
	v_mul_f32_e32 v21, v100, v6
	v_add_f32_e32 v8, 1.0, v8
	v_rcp_f32_e32 v8, v8
	v_mul_f32_e32 v9, v104, v9
	v_exp_f32_e32 v225, v9
	v_add_f32_e32 v6, 1.0, v22
	v_mul_f32_e32 v8, v104, v8
	v_exp_f32_e32 v228, v8
	v_add_f32_e32 v8, v11, v106
	v_exp_f32_e32 v8, v8
	v_fma_f32 v7, -v225, v225, 1.0
	v_max_f32_e32 v7, 0xda24260, v7
	v_mul_f32_e32 v9, v6, v7
	v_add_f32_e32 v8, 1.0, v8
	v_mul_f32_e32 v6, v6, v9
	v_rcp_f32_e32 v8, v8
	v_add_f32_e32 v12, v12, v106
	v_rsq_f32_e32 v6, v6
	v_exp_f32_e32 v12, v12
	v_add_f32_e32 v9, v26, v102
	v_exp_f32_e32 v9, v9
	v_add_f32_e32 v22, v27, v102
	v_mul_f32_e32 v8, v104, v8
	v_exp_f32_e32 v23, v22
	v_exp_f32_e32 v22, v8
	v_mul_f32_e32 v229, v7, v6
	v_add_f32_e32 v7, 1.0, v12
	v_fma_f32 v10, -v228, v228, 1.0
	v_rcp_f32_e32 v7, v7
	v_add_f32_e32 v9, 1.0, v9
	v_max_f32_e32 v10, 0xda24260, v10
	v_mul_f32_e32 v11, v9, v10
	v_mul_f32_e32 v8, v9, v11
	v_fma_f32 v11, -v22, v22, 1.0
	v_add_f32_e32 v9, 1.0, v23
	v_max_f32_e32 v11, 0xda24260, v11
	v_mul_f32_e32 v7, v104, v7
	v_mul_f32_e32 v23, v9, v11
	v_exp_f32_e32 v100, v7
	v_add_f32_e32 v7, v13, v106
	v_mul_f32_e32 v9, v9, v23
	v_exp_f32_e32 v7, v7
	v_rsq_f32_e32 v8, v8
	v_rsq_f32_e32 v9, v9
	v_add_f32_e32 v3, v3, v106
	v_add_f32_e32 v7, 1.0, v7
	v_mul_f32_e32 v230, v10, v8
	v_mul_f32_e32 v6, v11, v9
	v_rcp_f32_e32 v7, v7
	v_add_f32_e32 v10, v29, v102
	v_mul_f32_e32 v23, v98, v6
	v_add_f32_e32 v6, v28, v102
	v_exp_f32_e32 v10, v10
	v_exp_f32_e32 v6, v6
	v_mul_f32_e32 v7, v104, v7
	v_fma_f32 v8, -v100, v100, 1.0
	v_exp_f32_e32 v231, v7
	v_add_f32_e32 v7, 1.0, v10
	v_add_f32_e32 v10, v14, v106
	v_add_f32_e32 v6, 1.0, v6
	v_max_f32_e32 v8, 0xda24260, v8
	v_exp_f32_e32 v10, v10
	v_mul_f32_e32 v9, v6, v8
	v_mul_f32_e32 v6, v6, v9
	v_rsq_f32_e32 v6, v6
	v_add_f32_e32 v10, 1.0, v10
	v_rcp_f32_e32 v10, v10
	v_fma_f32 v9, -v231, v231, 1.0
	v_max_f32_e32 v9, 0xda24260, v9
	v_mul_f32_e32 v232, v8, v6
	v_add_f32_e32 v8, v15, v106
	v_mul_f32_e32 v11, v7, v9
	v_exp_f32_e32 v8, v8
	v_mul_f32_e32 v7, v7, v11
	v_mul_f32_e32 v10, v104, v10
	v_rsq_f32_e32 v7, v7
	v_add_f32_e32 v11, v30, v102
	v_exp_f32_e32 v98, v10
	v_exp_f32_e32 v11, v11
	v_add_f32_e32 v8, 1.0, v8
	v_rcp_f32_e32 v8, v8
	v_mul_f32_e32 v233, v9, v7
	v_fma_f32 v7, -v98, v98, 1.0
	v_add_f32_e32 v6, 1.0, v11
	v_max_f32_e32 v7, 0xda24260, v7
	v_exp_f32_e32 v3, v3
	v_mul_f32_e32 v9, v6, v7
	v_mul_f32_e32 v6, v6, v9
	v_mul_f32_e32 v8, v104, v8
	v_rsq_f32_e32 v6, v6
	v_add_f32_e32 v9, v31, v102
	v_exp_f32_e32 v25, v8
	v_exp_f32_e32 v9, v9
	v_add_f32_e32 v3, 1.0, v3
	v_rcp_f32_e32 v3, v3
	v_add_f32_e32 v2, v2, v106
	v_exp_f32_e32 v2, v2
	v_mul_f32_e32 v234, v7, v6
	v_fma_f32 v7, -v25, v25, 1.0
	v_add_f32_e32 v6, 1.0, v9
	v_max_f32_e32 v7, 0xda24260, v7
	v_add_f32_e32 v1, v1, v106
	v_mul_f32_e32 v8, v6, v7
	v_mul_f32_e32 v3, v104, v3
	v_exp_f32_e32 v1, v1
	v_mul_f32_e32 v6, v6, v8
	v_exp_f32_e32 v24, v3
	v_add_f32_e32 v3, v19, v102
	v_add_f32_e32 v2, 1.0, v2
	v_exp_f32_e32 v3, v3
	v_rsq_f32_e32 v6, v6
	v_rcp_f32_e32 v2, v2
	v_add_f32_e32 v1, 1.0, v1
	v_fma_f32 v8, -v24, v24, 1.0
	v_rcp_f32_e32 v1, v1
	v_max_f32_e32 v8, 0xda24260, v8
	v_add_f32_e32 v3, 1.0, v3
	v_mul_f32_e32 v6, v7, v6
	v_mul_f32_e32 v2, v104, v2
	v_add_f32_e32 v0, v0, v106
	v_mul_f32_e32 v9, v3, v8
	v_mul_f32_e32 v29, v96, v6
	v_exp_f32_e32 v2, v2
	v_add_f32_e32 v6, v18, v102
	v_exp_f32_e32 v0, v0
	v_mul_f32_e32 v3, v3, v9
	v_exp_f32_e32 v6, v6
	v_rsq_f32_e32 v3, v3
	v_mul_f32_e32 v1, v104, v1
	v_exp_f32_e32 v1, v1
	v_add_f32_e32 v9, v17, v102
	v_fma_f32 v7, -v2, v2, 1.0
	v_exp_f32_e32 v9, v9
	v_add_f32_e32 v0, 1.0, v0
	v_max_f32_e32 v7, 0xda24260, v7
	v_add_f32_e32 v6, 1.0, v6
	v_rcp_f32_e32 v0, v0
	v_mul_f32_e32 v3, v8, v3
	v_mul_f32_e32 v8, v6, v7
	v_mul_f32_e32 v6, v6, v8
	v_fma_f32 v8, -v1, v1, 1.0
	v_max_f32_e32 v8, 0xda24260, v8
	v_add_f32_e32 v9, 1.0, v9
	v_mul_f32_e32 v10, v9, v8
	v_mul_f32_e32 v0, v104, v0
	v_rsq_f32_e32 v6, v6
	v_mul_f32_e32 v9, v9, v10
	v_exp_f32_e32 v0, v0
	v_add_f32_e32 v10, v16, v102
	v_exp_f32_e32 v10, v10
	v_rsq_f32_e32 v9, v9
	v_mul_f32_e32 v19, v94, v3
	v_fma_f32 v11, -v0, v0, 1.0
	v_mul_f32_e32 v3, v7, v6
	v_mul_f32_e32 v18, v2, v19
	v_max_f32_e32 v11, 0xda24260, v11
	v_add_f32_e32 v10, 1.0, v10
	v_fmac_f32_e32 v18, v90, v3
	v_mul_f32_e32 v12, v10, v11
	v_mul_f32_e32 v6, v8, v9
	v_mul_f32_e32 v28, v24, v2
	v_mul_f32_e32 v17, v1, v18
	v_mul_f32_e32 v10, v10, v12
	v_fmac_f32_e32 v17, v84, v6
	v_mul_f32_e32 v27, v1, v28
	v_rsq_f32_e32 v10, v10
	v_mul_f32_e32 v16, v0, v17
	v_mul_f32_e32 v26, v0, v27
	ds_read_b128 v[0:3], v148 offset:23040
	ds_read_b128 v[218:221], v148 offset:23072
	v_mul_f32_e32 v7, v11, v10
	v_mul_f32_e32 v30, v4, v21
	v_fmac_f32_e32 v16, v76, v7
	v_fmac_f32_e32 v30, v86, v5
	v_mul_f32_e32 v84, v20, v4
	s_waitcnt lgkmcnt(1)
; #define LAS __attribute__((address_space(3)))
; template <int PASS>
; __device__ __forceinline__ void lru_item(Frame& F, const LAS bf16* lw, const LAS float* prm, const LAS float* cwl, LAS float* xs, LAS unsigned char* pf, int head, int item, int nitem) {
;     ...
;             f32x16 acc[2];
; #pragma unroll
;             for (int gt = 0; gt < 2; ++gt) {
;                 f32x16 a; for (int i = 0; i < 16; ++i) a[i] = 0.f;
;                 const LAS bf16* wb = lw + ((d * 2 + gt) * 64 + t + 32 * ct) * LRU_WROW + 8 * hh;
; #pragma unroll
;                 for (int ks = 0; ks < 4; ++ks) a = __builtin_amdgcn_mfma_f32_32x32x16_bf16(af[ks], *(const LAS bf16x8*)(wb + 16 * ks), a, 0, 0, 0);
;                 acc[gt] = a;
;             }
;             const int chl = t + 32 * ct, ch = head * 64 + chl;
;             float av[16], bv[16];
;             {
;                 const float br = prm[(d * 3 + 0) * 64 + chl], bi = prm[(d * 3 + 1) * 64 + chl], c8 = prm[(d * 3 + 2) * 64 + chl];
; #pragma unroll
;                 for (int rg = 0; rg < 16; ++rg) {
;                     const float rr = __builtin_amdgcn_rcpf(1.f + __builtin_amdgcn_exp2f(acc[0][rg] + br)), ei = 1.f + __builtin_amdgcn_exp2f(acc[1][rg] + bi);
;                     const float a = __builtin_amdgcn_exp2f(c8 * rr), om = fmaxf(fmaf(-a, a, 1.f), 1e-30f);
;                     av[rg] = a; bv[rg] = (om * __builtin_amdgcn_rsqf(om * ei * ei)) * xd[ct][rg];
;                 }
;             }
	v_mfma_f32_32x32x16_bf16 v[0:15], v[48:51], v[0:3], 0
	v_mul_f32_e32 v31, v222, v30
	v_fmac_f32_e32 v31, v78, v224
	v_mul_f32_e32 v86, v228, v23
	v_mul_f32_e32 v76, v217, v31
	v_fmac_f32_e32 v86, v80, v230
	v_mul_f32_e32 v94, v22, v228
	v_mul_f32_e32 v78, v222, v84
	s_waitcnt lgkmcnt(0)
	v_mfma_f32_32x32x16_bf16 v[0:15], v[52:55], v[218:221], v[0:15]
	ds_read_b128 v[218:221], v148 offset:23104
	v_fmac_f32_e32 v76, v70, v223
	v_mul_f32_e32 v80, v225, v86
	v_mul_f32_e32 v90, v225, v94
	ds_read_b128 v[222:225], v148 offset:23136
	v_mul_f32_e32 v96, v98, v29
	v_fmac_f32_e32 v80, v74, v229
	s_waitcnt lgkmcnt(1)
	v_mfma_f32_32x32x16_bf16 v[0:15], v[56:59], v[218:221], v[0:15]
	ds_read_b128 v[218:221], v148 offset:32256
	v_fmac_f32_e32 v96, v92, v234
	v_mul_f32_e32 v74, v226, v80
	v_mul_f32_e32 v92, v231, v96
	v_mul_f32_e32 v70, v217, v78
	v_fmac_f32_e32 v74, v72, v227
	v_mul_f32_e32 v72, v226, v90
	s_waitcnt lgkmcnt(1)
	v_mfma_f32_32x32x16_bf16 v[0:15], v[60:63], v[222:225], v[0:15]
	v_fmac_f32_e32 v92, v82, v233
	ds_read_b128 v[222:225], v148 offset:32288
	v_mul_f32_e32 v98, v25, v98
	v_mul_f32_e32 v231, v231, v98
	v_mul_f32_e32 v238, v100, v92
	v_fmac_f32_e32 v238, v68, v232
	v_mul_f32_e32 v68, v100, v231
	s_nop 4
	v_add_f32_e32 v82, v4, v107
	v_add_f32_e32 v102, v5, v107
	v_add_f32_e32 v104, v6, v107
	v_add_f32_e32 v106, v7, v107
	v_add_f32_e32 v217, v8, v107
	v_add_f32_e32 v226, v9, v107
	v_add_f32_e32 v227, v10, v107
	v_add_f32_e32 v228, v11, v107
	v_add_f32_e32 v229, v12, v107
	v_add_f32_e32 v230, v13, v107
	v_add_f32_e32 v233, v14, v107
	v_add_f32_e32 v234, v15, v107
	v_add_f32_e32 v235, v3, v107
	v_add_f32_e32 v236, v2, v107
	v_add_f32_e32 v237, v1, v107
	v_add_f32_e32 v107, v0, v107
	s_waitcnt lgkmcnt(1)
	v_mfma_f32_32x32x16_bf16 v[0:15], v[48:51], v[218:221], 0
	ds_read_b128 v[218:221], v148 offset:32352
	ds_bpermute_b32 v100, v128, v70
	v_exp_f32_e32 v107, v107
	ds_bpermute_b32 v49, v128, v26
	ds_bpermute_b32 v232, v128, v76
	ds_bpermute_b32 v48, v128, v16
	s_waitcnt lgkmcnt(3)
	v_cndmask_b32_e32 v51, v100, v70, vcc
	v_mfma_f32_32x32x16_bf16 v[0:15], v[52:55], v[222:225], v[0:15]
	ds_read_b128 v[52:55], v148 offset:32320
	v_add_f32_e32 v107, 1.0, v107
	v_rcp_f32_e32 v107, v107
	ds_bpermute_b32 v222, v128, v72
	v_fmac_f32_e32 v198, v209, v192
	v_fmac_f32_e32 v144, v117, v162
	v_cndmask_b32_e32 v153, v158, v142, vcc
	s_waitcnt lgkmcnt(1)
	v_mfma_f32_32x32x16_bf16 v[0:15], v[56:59], v[52:55], v[0:15]
	v_exp_f32_e32 v55, v82
	v_cndmask_b32_e32 v54, v70, v100, vcc
	s_waitcnt lgkmcnt(0)
	v_cndmask_b32_e32 v56, v222, v72, vcc
	v_cndmask_b32_e32 v58, v72, v222, vcc
	v_add_f32_e32 v55, 1.0, v55
	v_rcp_f32_e32 v55, v55
	ds_bpermute_b32 v53, v128, v74
	v_mfma_f32_32x32x16_bf16 v[0:15], v[60:63], v[218:221], v[0:15]
	v_exp_f32_e32 v61, v102
	v_mul_f32_e32 v55, v105, v55
	v_exp_f32_e32 v55, v55
	v_exp_f32_e32 v63, v104
	v_add_f32_e32 v61, 1.0, v61
	v_rcp_f32_e32 v61, v61
	v_fma_f32 v60, -v55, v55, 1.0
	s_nop 4
	v_add_f32_e32 v4, v4, v103
	v_exp_f32_e32 v4, v4
	v_max_f32_e32 v60, 0xda24260, v60
	v_mul_f32_e32 v61, v105, v61
	v_add_f32_e32 v5, v5, v103
	v_add_f32_e32 v4, 1.0, v4
	v_mul_f32_e32 v62, v4, v60
	v_mul_f32_e32 v4, v4, v62
	v_rsq_f32_e32 v4, v4
	v_exp_f32_e32 v61, v61
	v_exp_f32_e32 v5, v5
	v_add_f32_e32 v63, 1.0, v63
	v_mul_f32_e32 v4, v60, v4
	v_fma_f32 v60, -v61, v61, 1.0
	v_add_f32_e32 v5, 1.0, v5
	v_max_f32_e32 v60, 0xda24260, v60
	v_mul_f32_e32 v82, v5, v60
	v_mul_f32_e32 v5, v5, v82
	v_rsq_f32_e32 v5, v5
	v_rcp_f32_e32 v63, v63
	v_add_f32_e32 v6, v6, v103
	v_exp_f32_e32 v6, v6
	v_mul_f32_e32 v5, v60, v5
	v_exp_f32_e32 v60, v106
	v_mul_f32_e32 v63, v105, v63
	v_exp_f32_e32 v63, v63
	v_add_f32_e32 v7, v7, v103
	v_add_f32_e32 v60, 1.0, v60
	v_rcp_f32_e32 v60, v60
	v_fma_f32 v82, -v63, v63, 1.0
	v_exp_f32_e32 v7, v7
	v_add_f32_e32 v6, 1.0, v6
	v_mul_f32_e32 v60, v105, v60
	v_exp_f32_e32 v60, v60
	v_max_f32_e32 v82, 0xda24260, v82
	v_mul_f32_e32 v100, v6, v82
	v_mul_f32_e32 v6, v6, v100
	v_fma_f32 v100, -v60, v60, 1.0
	v_exp_f32_e32 v102, v217
	v_add_f32_e32 v7, 1.0, v7
	v_max_f32_e32 v100, 0xda24260, v100
	v_mul_f32_e32 v104, v7, v100
	v_mul_f32_e32 v7, v7, v104
	v_add_f32_e32 v102, 1.0, v102
	v_rsq_f32_e32 v7, v7
	v_rcp_f32_e32 v102, v102
	v_rsq_f32_e32 v6, v6
	v_add_f32_e32 v8, v8, v103
	v_mul_f32_e32 v7, v100, v7
	v_exp_f32_e32 v100, v226
	v_mul_f32_e32 v102, v105, v102
	v_exp_f32_e32 v102, v102
	v_exp_f32_e32 v8, v8
	v_add_f32_e32 v100, 1.0, v100
	v_rcp_f32_e32 v100, v100
	v_mul_f32_e32 v6, v82, v6
	v_fma_f32 v82, -v102, v102, 1.0
	v_add_f32_e32 v8, 1.0, v8
	v_max_f32_e32 v82, 0xda24260, v82
	v_mul_f32_e32 v104, v8, v82
	v_mul_f32_e32 v8, v8, v104
	v_mul_f32_e32 v100, v105, v100
	v_rsq_f32_e32 v8, v8
	v_add_f32_e32 v9, v9, v103
	v_exp_f32_e32 v100, v100
	v_exp_f32_e32 v9, v9
	v_mul_f32_e32 v8, v82, v8
	v_mul_f32_e32 v7, v101, v7
	v_fma_f32 v82, -v100, v100, 1.0
	v_add_f32_e32 v9, 1.0, v9
	v_max_f32_e32 v82, 0xda24260, v82
	v_mul_f32_e32 v104, v9, v82
	v_mul_f32_e32 v9, v9, v104
	v_rsq_f32_e32 v9, v9
	v_exp_f32_e32 v101, v227
	v_add_f32_e32 v10, v10, v103
	v_exp_f32_e32 v10, v10
	v_mul_f32_e32 v9, v82, v9
	v_exp_f32_e32 v82, v228
	v_add_f32_e32 v101, 1.0, v101
	v_rcp_f32_e32 v101, v101
	v_add_f32_e32 v11, v11, v103
	v_add_f32_e32 v82, 1.0, v82
	v_rcp_f32_e32 v82, v82
	v_mul_f32_e32 v101, v105, v101
	v_exp_f32_e32 v101, v101
	v_exp_f32_e32 v11, v11
	v_mul_f32_e32 v82, v105, v82
	v_exp_f32_e32 v82, v82
	v_fma_f32 v104, -v101, v101, 1.0
	v_add_f32_e32 v10, 1.0, v10
	v_max_f32_e32 v104, 0xda24260, v104
	v_mul_f32_e32 v106, v10, v104
	v_mul_f32_e32 v10, v10, v106
	v_fma_f32 v106, -v82, v82, 1.0
	v_add_f32_e32 v11, 1.0, v11
; template <int PASS>
; __device__ __forceinline__ void lru_item(Frame& F, const LAS bf16* lw, const LAS float* prm, const LAS float* cwl, LAS float* xs, LAS unsigned char* pf, int head, int item, int nitem) {
;     ...
;             {
;                 const float br = prm[(d * 3 + 0) * 64 + chl], bi = prm[(d * 3 + 1) * 64 + chl], c8 = prm[(d * 3 + 2) * 64 + chl];
; #pragma unroll
;                 for (int rg = 0; rg < 16; ++rg) {
;                     const float rr = __builtin_amdgcn_rcpf(1.f + __builtin_amdgcn_exp2f(acc[0][rg] + br)), ei = 1.f + __builtin_amdgcn_exp2f(acc[1][rg] + bi);
;                     const float a = __builtin_amdgcn_exp2f(c8 * rr), om = fmaxf(fmaf(-a, a, 1.f), 1e-30f);
;                     av[rg] = a; bv[rg] = (om * __builtin_amdgcn_rsqf(om * ei * ei)) * xd[ct][rg];
;                 }
;             }
;             float hl[16], cp[16], sA[4], sB[4];
; #pragma unroll
;             for (int q4 = 0; q4 < 4; ++q4) {
;                 if (d == 0) {
;                     hl[4 * q4] = bv[4 * q4]; cp[4 * q4] = av[4 * q4];
; #pragma unroll
;                     for (int i = 1; i < 4; ++i) { hl[4 * q4 + i] = av[4 * q4 + i] * hl[4 * q4 + i - 1] + bv[4 * q4 + i]; cp[4 * q4 + i] = av[4 * q4 + i] * cp[4 * q4 + i - 1]; }
;                     sA[q4] = cp[4 * q4 + 3]; sB[q4] = hl[4 * q4 + 3];
;                 } else {
;                     hl[4 * q4 + 3] = bv[4 * q4 + 3]; cp[4 * q4 + 3] = av[4 * q4 + 3];
; #pragma unroll
;                     for (int i = 2; i >= 0; --i) { hl[4 * q4 + i] = av[4 * q4 + i] * hl[4 * q4 + i + 1] + bv[4 * q4 + i]; cp[4 * q4 + i] = av[4 * q4 + i] * cp[4 * q4 + i + 1]; }
;                     sA[q4] = cp[4 * q4]; sB[q4] = hl[4 * q4];
;                 }
;             }
;             float Ae[4], Be[4], Ao[4], Bo[4];
; #pragma unroll
;             for (int q4 = 0; q4 < 4; ++q4) {
;                 const float oA = shx(sA[q4], 32, lane), oB = shx(sB[q4], 32, lane);
;                 Ae[q4] = hh ? oA : sA[q4]; Be[q4] = hh ? oB : sB[q4]; Ao[q4] = hh ? sA[q4] : oA; Bo[q4] = hh ? sB[q4] : oB;
;             }
;             if (PASS == 1) {
;                 float c = 0.f, P = 1.f;
;                 if (d == 0) {
; #pragma unroll
;                     for (int q4 = 0; q4 < 4; ++q4) { c = Ae[q4] * c + Be[q4]; c = Ao[q4] * c + Bo[q4]; P *= Ae[q4] * Ao[q4]; } }
;                 else {
; #pragma unroll
	v_max_f32_e32 v106, 0xda24260, v106
	v_mul_f32_e32 v148, v11, v106
	v_mul_f32_e32 v11, v11, v148
	v_rsq_f32_e32 v11, v11
	v_rsq_f32_e32 v10, v10
	v_exp_f32_e32 v217, v229
	v_add_f32_e32 v12, v12, v103
	v_mul_f32_e32 v11, v106, v11
	v_mul_f32_e32 v11, v99, v11
	v_exp_f32_e32 v99, v230
	v_mul_f32_e32 v10, v104, v10
	v_add_f32_e32 v104, 1.0, v217
	v_rcp_f32_e32 v104, v104
	v_add_f32_e32 v99, 1.0, v99
	v_rcp_f32_e32 v99, v99
	v_exp_f32_e32 v12, v12
	v_mul_f32_e32 v104, v105, v104
	v_exp_f32_e32 v104, v104
	v_exp_f32_e32 v217, v233
	v_mul_f32_e32 v99, v105, v99
	v_add_f32_e32 v13, v13, v103
	v_exp_f32_e32 v99, v99
	v_fma_f32 v106, -v104, v104, 1.0
	v_exp_f32_e32 v13, v13
	v_add_f32_e32 v12, 1.0, v12
	v_max_f32_e32 v106, 0xda24260, v106
	v_add_f32_e32 v217, 1.0, v217
	v_mul_f32_e32 v148, v12, v106
	v_rcp_f32_e32 v217, v217
	v_mul_f32_e32 v12, v12, v148
	v_fma_f32 v148, -v99, v99, 1.0
	v_add_f32_e32 v13, 1.0, v13
	v_max_f32_e32 v148, 0xda24260, v148
	v_mul_f32_e32 v218, v13, v148
	v_mul_f32_e32 v13, v13, v218
	v_mul_f32_e32 v217, v105, v217
	v_rsq_f32_e32 v12, v12
	v_rsq_f32_e32 v13, v13
	v_add_f32_e32 v14, v14, v103
	v_exp_f32_e32 v217, v217
	v_exp_f32_e32 v14, v14
	v_mul_f32_e32 v12, v106, v12
	v_mul_f32_e32 v13, v148, v13
	v_fma_f32 v106, -v217, v217, 1.0
	v_exp_f32_e32 v148, v234
	v_add_f32_e32 v14, 1.0, v14
	v_max_f32_e32 v106, 0xda24260, v106
	v_mul_f32_e32 v218, v14, v106
	v_mul_f32_e32 v14, v14, v218
	v_add_f32_e32 v148, 1.0, v148
	v_rsq_f32_e32 v14, v14
	v_rcp_f32_e32 v148, v148
	v_add_f32_e32 v15, v15, v103
	v_exp_f32_e32 v15, v15
	v_mul_f32_e32 v14, v106, v14
	v_exp_f32_e32 v106, v235
	v_mul_f32_e32 v148, v105, v148
	v_exp_f32_e32 v148, v148
	v_add_f32_e32 v15, 1.0, v15
	v_add_f32_e32 v106, 1.0, v106
	v_rcp_f32_e32 v106, v106
	v_fma_f32 v218, -v148, v148, 1.0
	v_max_f32_e32 v218, 0xda24260, v218
	v_mul_f32_e32 v219, v15, v218
	v_mul_f32_e32 v15, v15, v219
	v_mul_f32_e32 v106, v105, v106
	v_rsq_f32_e32 v15, v15
	v_exp_f32_e32 v106, v106
	v_add_f32_e32 v3, v3, v103
	v_exp_f32_e32 v3, v3
	v_mul_f32_e32 v15, v218, v15
	v_fma_f32 v218, -v106, v106, 1.0
	v_max_f32_e32 v218, 0xda24260, v218
	v_add_f32_e32 v3, 1.0, v3
	v_mul_f32_e32 v220, v3, v218
	v_mul_f32_e32 v3, v3, v220
	v_rsq_f32_e32 v3, v3
	v_exp_f32_e32 v219, v236
	v_mul_f32_e32 v15, v97, v15
	v_add_f32_e32 v2, v2, v103
	v_mul_f32_e32 v3, v218, v3
	v_exp_f32_e32 v218, v237
	v_add_f32_e32 v219, 1.0, v219
	v_rcp_f32_e32 v219, v219
	v_exp_f32_e32 v2, v2
	v_add_f32_e32 v218, 1.0, v218
	v_rcp_f32_e32 v218, v218
	v_mul_f32_e32 v97, v105, v219
	v_exp_f32_e32 v97, v97
	v_add_f32_e32 v1, v1, v103
	v_mul_f32_e32 v218, v105, v218
	v_exp_f32_e32 v218, v218
	v_exp_f32_e32 v1, v1
	v_mul_f32_e32 v105, v105, v107
	v_fma_f32 v219, -v97, v97, 1.0
	v_exp_f32_e32 v105, v105
	v_add_f32_e32 v0, v0, v103
	v_max_f32_e32 v219, 0xda24260, v219
	v_add_f32_e32 v2, 1.0, v2
	v_exp_f32_e32 v0, v0
	v_mul_f32_e32 v221, v2, v219
	v_fma_f32 v107, -v218, v218, 1.0
	v_mul_f32_e32 v2, v2, v221
	v_max_f32_e32 v107, 0xda24260, v107
	v_add_f32_e32 v1, 1.0, v1
	v_mul_f32_e32 v221, v1, v107
	v_rsq_f32_e32 v2, v2
	v_fma_f32 v103, -v105, v105, 1.0
	v_mul_f32_e32 v1, v1, v221
	v_max_f32_e32 v103, 0xda24260, v103
	v_add_f32_e32 v0, 1.0, v0
	v_rsq_f32_e32 v1, v1
	v_mul_f32_e32 v222, v0, v103
	v_mul_f32_e32 v0, v0, v222
	v_mul_f32_e32 v3, v95, v3
	v_rsq_f32_e32 v0, v0
	v_mul_f32_e32 v2, v219, v2
	v_mul_f32_e32 v95, v97, v3
	v_fmac_f32_e32 v95, v91, v2
	v_mul_f32_e32 v1, v107, v1
	v_mul_f32_e32 v91, v218, v95
	v_fmac_f32_e32 v91, v85, v1
	v_mul_f32_e32 v0, v103, v0
	v_mul_f32_e32 v85, v105, v91
	v_fmac_f32_e32 v85, v77, v0
	v_mul_f32_e32 v77, v63, v7
	v_fmac_f32_e32 v77, v87, v6
	v_mul_f32_e32 v6, v60, v63
	v_mul_f32_e32 v63, v61, v77
	v_fmac_f32_e32 v63, v79, v5
	v_mul_f32_e32 v5, v61, v6
	v_mul_f32_e32 v61, v55, v63
	v_fmac_f32_e32 v61, v71, v4
	v_mul_f32_e32 v4, v55, v5
	v_mul_f32_e32 v55, v101, v11
	v_fmac_f32_e32 v55, v81, v10
	v_mul_f32_e32 v71, v100, v55
	v_fmac_f32_e32 v71, v75, v9
	v_mul_f32_e32 v75, v102, v71
	v_fmac_f32_e32 v75, v73, v8
	v_mul_f32_e32 v73, v217, v15
	v_fmac_f32_e32 v73, v93, v14
	v_mul_f32_e32 v79, v99, v73
	v_mul_f32_e32 v14, v148, v217
	v_fmac_f32_e32 v79, v83, v13
	v_mul_f32_e32 v13, v99, v14
	v_mul_f32_e32 v81, v104, v79
	v_mul_f32_e32 v10, v82, v101
	v_fmac_f32_e32 v81, v69, v12
	v_mul_f32_e32 v83, v104, v13
	v_mul_f32_e32 v9, v100, v10
	ds_bpermute_b32 v103, v128, v83
	ds_bpermute_b32 v104, v128, v81
	v_mul_f32_e32 v8, v102, v9
	v_mul_f32_e32 v2, v106, v97
	ds_bpermute_b32 v99, v128, v8
	ds_bpermute_b32 v101, v128, v75
	v_mul_f32_e32 v1, v218, v2
	v_mul_f32_e32 v0, v105, v1
	ds_bpermute_b32 v69, v128, v4
	ds_bpermute_b32 v87, v128, v61
	ds_bpermute_b32 v59, v128, v68
	ds_bpermute_b32 v62, v128, v238
	ds_bpermute_b32 v12, v128, v0
	ds_bpermute_b32 v93, v128, v85
	s_waitcnt lgkmcnt(9)
	v_cndmask_b32_e32 v107, v103, v83, vcc
	s_waitcnt lgkmcnt(8)
	v_cndmask_b32_e32 v128, v104, v81, vcc
	v_cndmask_b32_e32 v103, v83, v103, vcc
	v_cndmask_b32_e32 v104, v81, v104, vcc
	v_fmac_f32_e32 v104, v120, v103
	s_waitcnt lgkmcnt(7)
	v_cndmask_b32_e32 v102, v99, v8, vcc
	s_waitcnt lgkmcnt(6)
	v_cndmask_b32_e32 v105, v101, v75, vcc
	v_cndmask_b32_e32 v99, v8, v99, vcc
	v_cndmask_b32_e32 v101, v75, v101, vcc
	v_fmac_f32_e32 v128, v107, v104
	v_fmac_f32_e32 v101, v99, v128
	s_waitcnt lgkmcnt(5)
	v_cndmask_b32_e32 v97, v69, v4, vcc
	s_waitcnt lgkmcnt(4)
	v_cndmask_b32_e32 v100, v87, v61, vcc
	v_cndmask_b32_e32 v69, v4, v69, vcc
	v_cndmask_b32_e32 v87, v61, v87, vcc
	v_fmac_f32_e32 v199, v210, v198
	v_fmac_f32_e32 v105, v102, v101
	v_fmac_f32_e32 v152, v163, v144
	v_cndmask_b32_e32 v158, v142, v158, vcc
	v_cndmask_b32_e32 v212, v213, v197, vcc
	v_cndmask_b32_e32 v205, v214, v196, vcc
	s_waitcnt lgkmcnt(3)
; template <int PASS>
; __device__ __forceinline__ void lru_item(Frame& F, const LAS bf16* lw, const LAS float* prm, const LAS float* cwl, LAS float* xs, LAS unsigned char* pf, int head, int item, int nitem) {
;     ...
;                 float cin[4];
;                 float c = lc[d][ct];
;                 if (d == 0) {
; #pragma unroll
;                     for (int q4 = 0; q4 < 4; ++q4) { const float c0 = c; c = Ae[q4] * c + Be[q4]; const float c1 = c; c = Ao[q4] * c + Bo[q4]; cin[q4] = hh ? c1 : c0; } }
;                 else {
; #pragma unroll
;     ...
; #pragma unroll
;                 for (int rg = 0; rg < 16; ++rg) { const float hv = hl[rg] + cp[rg] * cin[rg >> 2]; if (d == 0) ysum[ct][rg] = hv; else ysum[ct][rg] += hv; }
;             }
;         }
;     }
;     if (PASS == 2) {
; #pragma unroll
;         for (int ct = 0; ct < 2; ++ct)
; #pragma unroll
;             for (int rg = 0; rg < 16; ++rg) xs[((rg & 3) + 8 * (rg >> 2) + 4 * hh) * 68 + t + 32 * ct] = ysum[ct][rg];
	v_cndmask_b32_e32 v220, v59, v68, vcc
	s_waitcnt lgkmcnt(2)
	v_cndmask_b32_e32 v221, v62, v238, vcc
	v_cndmask_b32_e32 v59, v68, v59, vcc
	v_cndmask_b32_e32 v62, v238, v62, vcc
	v_fmac_f32_e32 v204, v211, v199
	v_fmac_f32_e32 v87, v69, v105
	v_fmac_f32_e32 v153, v164, v152
	v_cndmask_b32_e32 v213, v197, v213, vcc
	v_cndmask_b32_e32 v214, v196, v214, vcc
	s_waitcnt lgkmcnt(1)
	v_cndmask_b32_e32 v12, v0, v12, vcc
	v_fmac_f32_e32 v205, v212, v204
	v_fmac_f32_e32 v100, v97, v87
	v_fmac_f32_e32 v62, v118, v59
	v_fmac_f32_e32 v158, v165, v153
	v_cndmask_b32_e32 v216, v216, v207, vcc
	v_cndmask_b32_e32 v57, v53, v74, vcc
	v_cndmask_b32_e32 v53, v74, v53, vcc
	v_fmac_f32_e32 v214, v213, v205
	s_waitcnt lgkmcnt(0)
	v_fmac_f32_e32 v93, v12, v100
	v_fmac_f32_e32 v161, v166, v158
	v_fmac_f32_e32 v221, v220, v62
	v_fmac_f32_e32 v215, v216, v214
	v_cndmask_b32_e32 v12, v100, v93, vcc
	v_fmac_f32_e32 v168, v167, v161
	v_fmac_f32_e32 v53, v58, v221
	v_cndmask_b32_e32 v52, v76, v232, vcc
	v_cndmask_b32_e32 v103, v120, v104, vcc
	v_cndmask_b32_e32 v120, v215, v214, vcc
	v_fmac_f32_e32 v3, v106, v12
	v_fmac_f32_e32 v95, v2, v12
	v_fmac_f32_e32 v91, v1, v12
	v_fmac_f32_e32 v85, v0, v12
	v_cndmask_b32_e32 v12, v118, v62, vcc
	v_fmac_f32_e32 v169, v170, v168
	v_fmac_f32_e32 v57, v56, v53
	v_cndmask_b32_e32 v50, v232, v76, vcc
	v_fmac_f32_e32 v73, v14, v103
	v_fmac_f32_e32 v202, v203, v120
	v_fmac_f32_e32 v79, v13, v103
	v_fmac_f32_e32 v200, v201, v120
	v_fmac_f32_e32 v81, v83, v103
	v_fmac_f32_e32 v176, v175, v120
	v_fmac_f32_e32 v29, v25, v12
	v_cndmask_b32_e32 v25, v169, v168, vcc
	v_fmac_f32_e32 v52, v54, v57
	v_cndmask_b32_e32 v49, v26, v49, vcc
	v_add_f32_e32 v14, v202, v73
	v_add_f32_e32 v13, v200, v79
	v_add_f32_e32 v73, v176, v81
	v_cndmask_b32_e32 v79, v128, v101, vcc
	v_cndmask_b32_e32 v81, v205, v204, vcc
	v_fmac_f32_e32 v159, v160, v25
	v_fmac_f32_e32 v156, v157, v25
	v_fmac_f32_e32 v154, v155, v25
	v_fmac_f32_e32 v129, v127, v25
	v_cndmask_b32_e32 v25, v221, v53, vcc
	v_fmac_f32_e32 v50, v51, v52
	v_fmac_f32_e32 v55, v10, v79
	v_fmac_f32_e32 v194, v195, v81
	v_fmac_f32_e32 v23, v22, v25
	v_fmac_f32_e32 v86, v94, v25
	v_fmac_f32_e32 v80, v90, v25
	v_fmac_f32_e32 v74, v72, v25
	v_cndmask_b32_e32 v25, v57, v52, vcc
	v_fmac_f32_e32 v48, v49, v50
	v_add_f32_e32 v10, v194, v55
	v_cndmask_b32_e32 v55, v105, v87, vcc
	v_fmac_f32_e32 v21, v20, v25
	v_fmac_f32_e32 v30, v84, v25
	v_fmac_f32_e32 v31, v78, v25
	v_fmac_f32_e32 v76, v70, v25
	v_cndmask_b32_e32 v25, v50, v48, vcc
	v_fmac_f32_e32 v7, v60, v55
	v_fmac_f32_e32 v77, v6, v55
	v_fmac_f32_e32 v63, v5, v55
	v_fmac_f32_e32 v61, v4, v55
	v_cndmask_b32_e32 v55, v192, v119, vcc
	v_fmac_f32_e32 v19, v24, v25
	v_cndmask_b32_e32 v24, v144, v117, vcc
	v_cndmask_b32_e32 v60, v199, v198, vcc
	v_fmac_f32_e32 v178, v177, v55
	v_cndmask_b32_e32 v22, v161, v158, vcc
	v_cndmask_b32_e32 v20, v153, v152, vcc
	v_fmac_f32_e32 v16, v26, v25
	v_fmac_f32_e32 v131, v130, v24
	v_fmac_f32_e32 v15, v148, v103
	v_fmac_f32_e32 v206, v207, v120
	v_fmac_f32_e32 v11, v82, v79
	v_fmac_f32_e32 v196, v197, v81
	v_fmac_f32_e32 v71, v9, v79
	v_fmac_f32_e32 v191, v193, v81
	v_fmac_f32_e32 v75, v8, v79
	v_fmac_f32_e32 v174, v173, v81
	v_fmac_f32_e32 v189, v190, v60
	v_fmac_f32_e32 v187, v188, v60
	v_fmac_f32_e32 v185, v186, v60
	v_fmac_f32_e32 v172, v171, v60
	v_fmac_f32_e32 v183, v184, v55
	v_fmac_f32_e32 v181, v182, v55
	v_fmac_f32_e32 v179, v180, v55
	v_add_f32_e32 v0, v178, v85
	v_fmac_f32_e32 v96, v98, v12
	v_fmac_f32_e32 v92, v231, v12
	v_fmac_f32_e32 v238, v68, v12
	v_fmac_f32_e32 v150, v151, v22
	v_fmac_f32_e32 v147, v149, v22
	v_fmac_f32_e32 v145, v146, v22
	v_fmac_f32_e32 v126, v125, v22
	v_fmac_f32_e32 v142, v143, v20
	v_fmac_f32_e32 v140, v141, v20
	v_fmac_f32_e32 v138, v139, v20
	v_fmac_f32_e32 v124, v123, v20
	v_fmac_f32_e32 v136, v137, v24
	v_fmac_f32_e32 v18, v28, v25
	v_fmac_f32_e32 v134, v135, v24
	v_fmac_f32_e32 v17, v27, v25
	v_fmac_f32_e32 v132, v133, v24
	v_add_f32_e32 v16, v131, v16
	v_add_f32_e32 v15, v206, v15
	v_add_f32_e32 v11, v196, v11
	v_add_f32_e32 v9, v191, v71
	v_add_f32_e32 v8, v174, v75
	v_add_f32_e32 v7, v189, v7
	v_add_f32_e32 v6, v187, v77
	v_add_f32_e32 v5, v185, v63
	v_add_f32_e32 v4, v172, v61
	v_add_f32_e32 v3, v183, v3
	v_add_f32_e32 v2, v181, v95
	v_add_f32_e32 v1, v179, v91
	v_add_f32_e32 v29, v159, v29
	v_add_f32_e32 v55, v156, v96
	v_add_f32_e32 v59, v154, v92
	v_add_f32_e32 v12, v129, v238
	v_add_f32_e32 v23, v150, v23
	v_add_f32_e32 v58, v147, v86
	v_add_f32_e32 v60, v145, v80
	v_add_f32_e32 v22, v126, v74
	v_add_f32_e32 v21, v142, v21
	v_add_f32_e32 v30, v140, v30
	v_add_f32_e32 v31, v138, v31
	v_add_f32_e32 v20, v124, v76
	v_add_f32_e32 v19, v136, v19
	v_add_f32_e32 v18, v134, v18
	v_add_f32_e32 v17, v132, v17
	ds_write2_b32 v109, v16, v0 offset1:32
	ds_write2_b32 v109, v17, v1 offset0:68 offset1:100
	ds_write2_b32 v109, v18, v2 offset0:136 offset1:168
	ds_write2_b32 v109, v19, v3 offset0:204 offset1:236
	ds_write2_b32 v110, v20, v4 offset0:32 offset1:64
	ds_write2_b32 v110, v31, v5 offset0:100 offset1:132
	ds_write2_b32 v110, v30, v6 offset0:168 offset1:200
	ds_write2_b32 v112, v21, v7 offset0:108 offset1:140
	ds_write2_b32 v111, v22, v8 offset0:64 offset1:96
	ds_write2_b32 v111, v60, v9 offset0:132 offset1:164
	ds_write2_b32 v111, v58, v10 offset0:200 offset1:232
	ds_write2_b32 v113, v23, v11 offset0:12 offset1:44
	ds_write2_b32 v121, v12, v73 offset0:96 offset1:128
	ds_write2_b32 v121, v59, v13 offset0:164 offset1:196
	ds_write2_b32 v88, v55, v14 offset0:104 offset1:136
	ds_write2_b32 v122, v29, v15 offset0:44 offset1:76
	s_waitcnt lgkmcnt(0)
; #define LAS __attribute__((address_space(3)))
; __device__ __forceinline__ unsigned cvt_pk_bf16(float lo, float hi) { unsigned r; asm volatile("v_cvt_pk_bf16_f32 %0, %1, %2" : "=v"(r) : "v"(lo), "v"(hi)); return r; }
; __device__ __forceinline__ float bf_lo(unsigned w) { return __uint_as_float(w << 16); }
; __device__ __forceinline__ float bf_hi(unsigned w) { return __uint_as_float(w & 0xffff0000u); }
; #define LDS_WAIT() asm volatile("s_waitcnt lgkmcnt(0)" ::: "memory")
; template <int PASS>
; __device__ __forceinline__ void lru_item(Frame& F, const LAS bf16* lw, const LAS float* prm, const LAS float* cwl, LAS float* xs, LAS unsigned char* pf, int head, int item, int nitem) {
;     ...
;         LDS_WAIT(); asm volatile("" ::: "memory");
;         bf16* yb = (bf16*)(F.ws + WS_YB) + tok * LRUW + head * 64;
; #pragma unroll
;         for (int ks = 0; ks < 4; ++ks) {
;             const int c0 = 16 * ks + 8 * hh; const u32x4 g4 = gq[ks];
;             const f32x4 y0 = *(const LAS f32x4*)(xs + t * 68 + c0), y1 = *(const LAS f32x4*)(xs + t * 68 + c0 + 4);
;             u32x4 o; o.x = cvt_pk_bf16(y0[0] * bf_lo(g4.x), y0[1] * bf_hi(g4.x)); o.y = cvt_pk_bf16(y0[2] * bf_lo(g4.y), y0[3] * bf_hi(g4.y));
;             o.z = cvt_pk_bf16(y1[0] * bf_lo(g4.z), y1[1] * bf_hi(g4.z)); o.w = cvt_pk_bf16(y1[2] * bf_lo(g4.w), y1[3] * bf_hi(g4.w));
;             *(u32x4*)(yb + c0) = o;
;         }
	v_lshl_add_u32 v10, v116, 5, v108
	ds_read_b128 v[0:3], v10 offset:40960
	ds_read_b128 v[4:7], v10 offset:40976
	s_waitcnt vmcnt(0)
	v_lshlrev_b32_e32 v11, 16, v44
	v_lshl_add_u64 v[8:9], s[10:11], 0, v[66:67]
	v_lshl_add_u64 v[8:9], v[8:9], 0, v[64:65]
	s_waitcnt lgkmcnt(1)
	v_mul_f32_e32 v0, v0, v11
	v_and_b32_e32 v11, 0xffff0000, v44
	v_mul_f32_e32 v1, v1, v11
	v_cvt_pk_bf16_f32 v0, v0, v1
	v_lshlrev_b32_e32 v1, 16, v45
	v_mul_f32_e32 v1, v2, v1
	v_and_b32_e32 v2, 0xffff0000, v45
	v_mul_f32_e32 v2, v3, v2
	v_cvt_pk_bf16_f32 v1, v1, v2
	v_lshlrev_b32_e32 v2, 16, v46
	v_and_b32_e32 v3, 0xffff0000, v46
	s_waitcnt lgkmcnt(0)
	v_mul_f32_e32 v2, v4, v2
	v_mul_f32_e32 v3, v5, v3
	v_cvt_pk_bf16_f32 v2, v2, v3
	v_lshlrev_b32_e32 v3, 16, v47
	v_and_b32_e32 v4, 0xffff0000, v47
	v_mul_f32_e32 v3, v6, v3
	v_mul_f32_e32 v4, v7, v4
	v_cvt_pk_bf16_f32 v3, v3, v4
	ds_read_b128 v[4:7], v10 offset:41024
	v_lshlrev_b32_e32 v11, 16, v40
	global_store_dwordx4 v[8:9], v[0:3], off
	ds_read_b128 v[0:3], v10 offset:41040
	s_andn2_b64 vcc, exec, s[12:13]
	s_waitcnt lgkmcnt(1)
	v_mul_f32_e32 v4, v4, v11
	v_and_b32_e32 v11, 0xffff0000, v40
	v_mul_f32_e32 v5, v5, v11
	v_cvt_pk_bf16_f32 v4, v4, v5
	v_lshlrev_b32_e32 v5, 16, v41
	v_mul_f32_e32 v5, v6, v5
	v_and_b32_e32 v6, 0xffff0000, v41
	v_mul_f32_e32 v6, v7, v6
	v_cvt_pk_bf16_f32 v5, v5, v6
	v_lshlrev_b32_e32 v6, 16, v42
	s_waitcnt lgkmcnt(0)
	v_mul_f32_e32 v0, v0, v6
	v_and_b32_e32 v6, 0xffff0000, v42
	v_mul_f32_e32 v1, v1, v6
	v_cvt_pk_bf16_f32 v6, v0, v1
	v_lshlrev_b32_e32 v0, 16, v43
	v_and_b32_e32 v1, 0xffff0000, v43
	v_mul_f32_e32 v0, v2, v0
	v_mul_f32_e32 v1, v3, v1
	v_cvt_pk_bf16_f32 v7, v0, v1
	ds_read_b128 v[0:3], v10 offset:41088
	v_lshlrev_b32_e32 v11, 16, v36
	global_store_dwordx4 v[8:9], v[4:7], off offset:32
	ds_read_b128 v[4:7], v10 offset:41104
	s_waitcnt lgkmcnt(1)
	v_mul_f32_e32 v0, v0, v11
	v_and_b32_e32 v11, 0xffff0000, v36
	v_mul_f32_e32 v1, v1, v11
	v_cvt_pk_bf16_f32 v0, v0, v1
	v_lshlrev_b32_e32 v1, 16, v37
	v_mul_f32_e32 v1, v2, v1
	v_and_b32_e32 v2, 0xffff0000, v37
	v_mul_f32_e32 v2, v3, v2
	v_cvt_pk_bf16_f32 v1, v1, v2
	v_lshlrev_b32_e32 v2, 16, v38
	v_and_b32_e32 v3, 0xffff0000, v38
	s_waitcnt lgkmcnt(0)
	v_mul_f32_e32 v2, v4, v2
	v_mul_f32_e32 v3, v5, v3
	v_cvt_pk_bf16_f32 v2, v2, v3
	v_lshlrev_b32_e32 v3, 16, v39
	v_and_b32_e32 v4, 0xffff0000, v39
	v_mul_f32_e32 v3, v6, v3
	v_mul_f32_e32 v4, v7, v4
	v_cvt_pk_bf16_f32 v3, v3, v4
	ds_read_b128 v[4:7], v10 offset:41152
	global_store_dwordx4 v[8:9], v[0:3], off offset:64
	ds_read_b128 v[0:3], v10 offset:41168
	v_lshlrev_b32_e32 v10, 16, v32
	s_waitcnt lgkmcnt(1)
	v_mul_f32_e32 v4, v4, v10
	v_and_b32_e32 v10, 0xffff0000, v32
	v_mul_f32_e32 v5, v5, v10
	v_cvt_pk_bf16_f32 v4, v4, v5
	v_lshlrev_b32_e32 v5, 16, v33
	v_mul_f32_e32 v5, v6, v5
	v_and_b32_e32 v6, 0xffff0000, v33
	v_mul_f32_e32 v6, v7, v6
	v_cvt_pk_bf16_f32 v5, v5, v6
	v_lshlrev_b32_e32 v6, 16, v34
	s_waitcnt lgkmcnt(0)
	v_mul_f32_e32 v0, v0, v6
	v_and_b32_e32 v6, 0xffff0000, v34
	v_mul_f32_e32 v1, v1, v6
	v_cvt_pk_bf16_f32 v6, v0, v1
	v_lshlrev_b32_e32 v0, 16, v35
	v_and_b32_e32 v1, 0xffff0000, v35
	v_mul_f32_e32 v0, v2, v0
	v_mul_f32_e32 v1, v3, v1
	v_cvt_pk_bf16_f32 v7, v0, v1
	global_store_dwordx4 v[8:9], v[4:7], off offset:96
	s_waitcnt lgkmcnt(0)
	s_cbranch_vccz .LBB0_918
